# batched weight-transpose queue items 8 per dequeue in mixer and prologue, hoisted their loads, GEMM DMAs issued early in each K-tile
# speedup vs baseline: 1.1564x; 1.0347x over previous
.LBB0_31:
	s_or_b64 exec, exec, s[20:21]
	s_waitcnt lgkmcnt(0)
	s_barrier
	ds_read_b32 v0, v13 offset:53264
	s_movk_i32 s0, 0x287
	s_mov_b64 s[20:21], -1
	s_waitcnt lgkmcnt(0)
	v_cmp_lt_i32_e32 vcc, s0, v0
	v_readfirstlane_b32 s34, v0
	s_cbranch_vccnz .LBB0_26
	s_cmpk_gt_i32 s34, 0x11f
	s_cbranch_scc0 .LBB0_54
	s_sub_u32 s34, s34, 288
	s_lshl_b32 s34, s34, 3
	s_add_u32 s34, s34, 288
	s_mov_b32 s53, 0
.Lptr_again:
	s_mov_b64 s[20:21], -1
	s_add_i32 s35, s34, 0xfffffee0
	s_cmpk_lt_u32 s35, 0x580
	s_cbranch_scc1 .LBB0_38
	s_cmpk_gt_u32 s35, 0x83f
	s_cbranch_scc0 .LBB0_36
	s_add_i32 s35, s34, 0x17a0
	s_mov_b64 s[20:21], 0

.LBB0_45:
	s_and_b32 s26, 0xffff, s37
	v_cvt_f32_u32_e32 v0, s26
	s_and_b32 s26, 0xffff, s36
	v_cvt_f32_u32_e32 v1, s26
	v_mov_b32_e32 v8, v128
	v_rcp_iflag_f32_e32 v2, v0
	v_mov_b32_e32 v4, 0
	v_ashrrev_i32_e32 v9, 4, v8
	v_mul_f32_e32 v2, v1, v2
	v_trunc_f32_e32 v2, v2
	v_cvt_u32_f32_e32 v3, v2
	v_fma_f32 v1, -v2, v0, v1
	v_cmp_ge_f32_e64 s[26:27], |v1|, v0
	s_cmp_lg_u64 s[26:27], 0
	v_readfirstlane_b32 s26, v3
	s_addc_u32 s26, s26, 0
	s_and_b32 s27, s26, 0xffff
	s_mul_i32 s35, s26, s37
	s_lshl_b32 s26, s27, 6
	s_sub_i32 s27, s36, s35
	s_lshl_b32 s27, s27, 6
	v_lshlrev_b32_e32 v0, 2, v8
	s_and_b32 s27, s27, 0xffc0
	v_and_b32_e32 v1, 60, v0
	v_or_b32_e32 v0, s27, v1
	v_lshlrev_b32_e32 v12, 2, v0
	v_cmp_gt_u32_e32 vcc, s0, v0
	v_lshl_add_u64 v[6:7], s[24:25], 0, v[12:13]
	v_mov_b32_e32 v168, 0
	v_mov_b32_e32 v169, 0
	v_mov_b32_e32 v170, 0
	v_mov_b32_e32 v171, 0
	v_mov_b32_e32 v172, 0
	v_mov_b32_e32 v173, 0
	v_mov_b32_e32 v174, 0
	v_mov_b32_e32 v175, 0
	v_mov_b32_e32 v176, 0
	v_mov_b32_e32 v177, 0
	v_mov_b32_e32 v178, 0
	v_mov_b32_e32 v179, 0
	v_mov_b32_e32 v180, 0
	v_mov_b32_e32 v181, 0
	v_mov_b32_e32 v182, 0
	v_mov_b32_e32 v183, 0
	v_mov_b32_e32 v185, 0
	s_lshl_b32 s50, s0, 6
	s_mov_b32 s51, 0
	s_and_saveexec_b64 s[24:25], vcc
	s_cbranch_execz .Ltrp_0
	v_add_u32_e32 v184, s26, v9
	v_mul_lo_u32 v184, v184, s0
	v_lshlrev_b32_e32 v184, 2, v184
	v_lshl_add_u64 v[186:187], v[184:185], 0, v[6:7]
	global_load_dwordx4 v[168:171], v[186:187], off nt
	v_lshl_add_u64 v[186:187], v[186:187], 0, s[50:51]
	global_load_dwordx4 v[172:175], v[186:187], off nt
	v_lshl_add_u64 v[186:187], v[186:187], 0, s[50:51]
	global_load_dwordx4 v[176:179], v[186:187], off nt
	v_lshl_add_u64 v[186:187], v[186:187], 0, s[50:51]
	global_load_dwordx4 v[180:183], v[186:187], off nt
.Ltrp_0:
	s_or_b64 exec, exec, s[24:25]
	v_lshlrev_b32_e32 v1, 2, v1
	v_mul_lo_u32 v10, v9, s28
	v_add_u32_e32 v10, v1, v10
	s_waitcnt vmcnt(0)
	ds_write2_b32 v10, v168, v169 offset1:1
	ds_write2_b32 v10, v170, v171 offset0:2 offset1:3
	v_add_u32_e32 v4, 0x1040, v10
	ds_write2_b32 v4, v172, v173 offset1:1
	v_add_u32_e32 v0, 0x1048, v10
	ds_write2_b32 v0, v174, v175 offset1:1
	v_add_u32_e32 v1, 0x2080, v10
	ds_write2_b32 v1, v176, v177 offset1:1
	v_add_u32_e32 v2, 0x2088, v10
	ds_write2_b32 v2, v178, v179 offset1:1
	v_add_u32_e32 v3, 0x30c0, v10
	ds_write2_b32 v3, v180, v181 offset1:1
	v_add_u32_e32 v5, 0x30c8, v10
	ds_write2_b32 v5, v182, v183 offset1:1
	v_lshlrev_b32_e32 v0, 4, v8
	v_ashrrev_i32_e32 v12, 2, v8
	v_and_b32_e32 v22, 48, v0
	v_and_b32_e32 v0, -4, v8
	v_mad_u32_u24 v14, v22, s28, v0
	v_add_u32_e32 v12, s27, v12
	s_waitcnt lgkmcnt(0)
	s_barrier
	ds_read2_b32 v[0:1], v14 offset1:65
	ds_read2_b32 v[2:3], v14 offset0:130 offset1:195
	v_ashrrev_i32_e32 v20, 31, v12
	v_mul_lo_u32 v23, s22, v20
	v_mul_lo_u32 v24, s23, v12
	v_mad_u64_u32 v[20:21], s[22:23], s22, v12, 0
	v_add3_u32 v21, v21, v23, v24
	v_add_u32_e32 v6, 0x400, v14
	v_lshl_add_u64 v[20:21], v[20:21], 1, s[20:21]
	s_lshl_b32 s0, s26, 1
	ds_read2_b32 v[4:5], v6 offset0:4 offset1:69
	ds_read2_b32 v[6:7], v6 offset0:134 offset1:199
	v_lshl_add_u64 v[20:21], v[20:21], 0, s[0:1]
	v_lshlrev_b32_e32 v12, 1, v22
	v_lshl_add_u64 v[20:21], v[20:21], 0, v[12:13]
	s_waitcnt lgkmcnt(2)
	v_and_b32_sdwa v12, v2, v18 dst_sel:DWORD dst_unused:UNUSED_PAD src0_sel:WORD_1 src1_sel:DWORD
	v_and_b32_sdwa v22, v0, v18 dst_sel:DWORD dst_unused:UNUSED_PAD src0_sel:WORD_1 src1_sel:DWORD
	v_add3_u32 v2, v2, v12, s29
	v_and_b32_sdwa v12, v3, v18 dst_sel:DWORD dst_unused:UNUSED_PAD src0_sel:WORD_1 src1_sel:DWORD
	v_add3_u32 v0, v0, v22, s29
	v_and_b32_sdwa v22, v1, v18 dst_sel:DWORD dst_unused:UNUSED_PAD src0_sel:WORD_1 src1_sel:DWORD
	v_add3_u32 v3, v3, v12, s29
	v_add3_u32 v1, v1, v22, s29
	v_and_b32_e32 v3, 0xffff0000, v3
	v_add_u32_e32 v10, 0x800, v14
	v_and_b32_e32 v12, 0xffff0000, v1
	v_or_b32_sdwa v1, v3, v2 dst_sel:DWORD dst_unused:UNUSED_PAD src0_sel:DWORD src1_sel:WORD_1
	s_waitcnt lgkmcnt(0)
	v_and_b32_sdwa v2, v6, v18 dst_sel:DWORD dst_unused:UNUSED_PAD src0_sel:WORD_1 src1_sel:DWORD
	v_and_b32_sdwa v3, v4, v18 dst_sel:DWORD dst_unused:UNUSED_PAD src0_sel:WORD_1 src1_sel:DWORD
	ds_read2_b32 v[8:9], v10 offset0:8 offset1:73
	ds_read2_b32 v[10:11], v10 offset0:138 offset1:203
	v_add3_u32 v4, v4, v3, s29
	v_add3_u32 v2, v6, v2, s29
	v_and_b32_sdwa v3, v7, v18 dst_sel:DWORD dst_unused:UNUSED_PAD src0_sel:WORD_1 src1_sel:DWORD
	v_and_b32_sdwa v6, v5, v18 dst_sel:DWORD dst_unused:UNUSED_PAD src0_sel:WORD_1 src1_sel:DWORD
	v_add3_u32 v3, v7, v3, s29
	v_add3_u32 v5, v5, v6, s29
	v_and_b32_e32 v3, 0xffff0000, v3
	v_and_b32_e32 v5, 0xffff0000, v5
	v_add_u32_e32 v16, 0xc00, v14
	v_or_b32_sdwa v0, v12, v0 dst_sel:DWORD dst_unused:UNUSED_PAD src0_sel:DWORD src1_sel:WORD_1
	v_or_b32_sdwa v3, v3, v2 dst_sel:DWORD dst_unused:UNUSED_PAD src0_sel:DWORD src1_sel:WORD_1
	v_or_b32_sdwa v2, v5, v4 dst_sel:DWORD dst_unused:UNUSED_PAD src0_sel:DWORD src1_sel:WORD_1
	ds_read2_b32 v[14:15], v16 offset0:12 offset1:77
	ds_read2_b32 v[16:17], v16 offset0:142 offset1:207
	global_store_dwordx4 v[20:21], v[0:3], off
	s_mov_b64 s[20:21], 0
	s_waitcnt lgkmcnt(1)
	v_and_b32_sdwa v5, v15, v18 dst_sel:DWORD dst_unused:UNUSED_PAD src0_sel:WORD_1 src1_sel:DWORD
	v_and_b32_sdwa v1, v8, v18 dst_sel:DWORD dst_unused:UNUSED_PAD src0_sel:WORD_1 src1_sel:DWORD
	v_add3_u32 v2, v8, v1, s29
	v_and_b32_sdwa v1, v11, v18 dst_sel:DWORD dst_unused:UNUSED_PAD src0_sel:WORD_1 src1_sel:DWORD
	v_and_b32_sdwa v3, v9, v18 dst_sel:DWORD dst_unused:UNUSED_PAD src0_sel:WORD_1 src1_sel:DWORD
	v_and_b32_sdwa v0, v10, v18 dst_sel:DWORD dst_unused:UNUSED_PAD src0_sel:WORD_1 src1_sel:DWORD
	v_add3_u32 v1, v11, v1, s29
	v_add3_u32 v3, v9, v3, s29
	v_add3_u32 v0, v10, v0, s29
	v_and_b32_e32 v1, 0xffff0000, v1
	v_and_b32_e32 v3, 0xffff0000, v3
	v_or_b32_sdwa v1, v1, v0 dst_sel:DWORD dst_unused:UNUSED_PAD src0_sel:DWORD src1_sel:WORD_1
	v_or_b32_sdwa v0, v3, v2 dst_sel:DWORD dst_unused:UNUSED_PAD src0_sel:DWORD src1_sel:WORD_1
	v_and_b32_sdwa v3, v14, v18 dst_sel:DWORD dst_unused:UNUSED_PAD src0_sel:WORD_1 src1_sel:DWORD
	v_add3_u32 v4, v14, v3, s29
	s_waitcnt lgkmcnt(0)
	v_and_b32_sdwa v3, v17, v18 dst_sel:DWORD dst_unused:UNUSED_PAD src0_sel:WORD_1 src1_sel:DWORD
	v_and_b32_sdwa v2, v16, v18 dst_sel:DWORD dst_unused:UNUSED_PAD src0_sel:WORD_1 src1_sel:DWORD
	v_add3_u32 v3, v17, v3, s29
	v_add3_u32 v5, v15, v5, s29
	v_add3_u32 v2, v16, v2, s29
	v_and_b32_e32 v3, 0xffff0000, v3
	v_and_b32_e32 v5, 0xffff0000, v5
	v_or_b32_sdwa v3, v3, v2 dst_sel:DWORD dst_unused:UNUSED_PAD src0_sel:DWORD src1_sel:WORD_1
	v_or_b32_sdwa v2, v5, v4 dst_sel:DWORD dst_unused:UNUSED_PAD src0_sel:DWORD src1_sel:WORD_1
	global_store_dwordx4 v[20:21], v[0:3], off offset:16
	s_barrier
	s_add_u32 s53, s53, 1
	s_cmp_lt_u32 s53, 8
	s_cbranch_scc0 .Lptr_done
	s_add_u32 s34, s34, 1
	s_branch .Lptr_again
.Lptr_done:
.LBB0_54:
	s_and_b64 vcc, exec, s[20:21]
	s_cbranch_vccz .LBB0_25
	v_mov_b32_e32 v20, v128
	s_movk_i32 s0, 0xbff
	s_nop 0
	v_cmp_lt_i32_e32 vcc, s0, v20
	v_lshlrev_b32_e32 v21, 2, v20
	s_and_saveexec_b64 s[20:21], vcc
	s_xor_b64 s[20:21], exec, s[20:21]
	v_lshlrev_b32_e32 v21, 2, v20
	s_andn2_saveexec_b64 s[20:21], s[20:21]
	s_cbranch_execz .LBB0_65
	s_mov_b64 s[22:23], 0
	v_mov_b32_e32 v2, v21
	v_mov_b32_e32 v3, v20
	s_branch .LBB0_60

.LBB0_66:
	v_lshl_add_u64 v[16:17], v[14:15], 0, s[22:23]
	s_mov_b32 s50, 0x90000
	s_mov_b32 s51, 0
	v_mov_b32_e32 v232, v16
	v_mov_b32_e32 v233, v17
	global_load_dwordx4 v[168:171], v[232:233], off nt
	v_lshl_add_u64 v[232:233], v[232:233], 0, s[50:51]
	global_load_dwordx4 v[172:175], v[232:233], off nt
	v_lshl_add_u64 v[232:233], v[232:233], 0, s[50:51]
	global_load_dwordx4 v[176:179], v[232:233], off nt
	v_lshl_add_u64 v[232:233], v[232:233], 0, s[50:51]
	global_load_dwordx4 v[180:183], v[232:233], off nt
	v_lshl_add_u64 v[232:233], v[232:233], 0, s[50:51]
	global_load_dwordx4 v[184:187], v[232:233], off nt
	v_lshl_add_u64 v[232:233], v[232:233], 0, s[50:51]
	global_load_dwordx4 v[188:191], v[232:233], off nt
	v_lshl_add_u64 v[232:233], v[232:233], 0, s[50:51]
	global_load_dwordx4 v[192:195], v[232:233], off nt
	v_lshl_add_u64 v[232:233], v[232:233], 0, s[50:51]
	global_load_dwordx4 v[196:199], v[232:233], off nt
	v_lshl_add_u64 v[232:233], v[232:233], 0, s[50:51]
	global_load_dwordx4 v[200:203], v[232:233], off nt
	v_lshl_add_u64 v[232:233], v[232:233], 0, s[50:51]
	global_load_dwordx4 v[204:207], v[232:233], off nt
	v_lshl_add_u64 v[232:233], v[232:233], 0, s[50:51]
	global_load_dwordx4 v[208:211], v[232:233], off nt
	v_lshl_add_u64 v[232:233], v[232:233], 0, s[50:51]
	global_load_dwordx4 v[212:215], v[232:233], off nt
	v_lshl_add_u64 v[232:233], v[232:233], 0, s[50:51]
	global_load_dwordx4 v[216:219], v[232:233], off nt
	v_lshl_add_u64 v[232:233], v[232:233], 0, s[50:51]
	global_load_dwordx4 v[220:223], v[232:233], off nt
	v_lshl_add_u64 v[232:233], v[232:233], 0, s[50:51]
	global_load_dwordx4 v[224:227], v[232:233], off nt
	v_lshl_add_u64 v[232:233], v[232:233], 0, s[50:51]
	global_load_dwordx4 v[228:231], v[232:233], off nt
	ds_read2_b32 v[28:29], v22 offset1:16
	s_mov_b32 s21, 0x90000
	s_add_u32 s22, s22, 0x900000
	s_addc_u32 s23, s23, 0
	s_cmp_eq_u32 s22, 0x2400000
	s_waitcnt vmcnt(15) lgkmcnt(0)
	v_mov_b32_e32 v24, v168
	v_mov_b32_e32 v25, v169
	v_mov_b32_e32 v26, v170
	v_mov_b32_e32 v27, v171
	v_pk_fma_f32 v[30:31], v[24:25], v[28:29], v[8:9] op_sel_hi:[1,0,1]
	v_add_u32_e32 v8, 0x1000, v22
	ds_read2_b32 v[32:33], v8 offset1:16
	v_pk_fma_f32 v[10:11], v[26:27], v[28:29], v[10:11] op_sel_hi:[1,0,1]
	v_mov_b32_e32 v28, v29
	s_waitcnt lgkmcnt(0)
	v_pk_fma_f32 v[34:35], v[24:25], v[32:33], v[4:5] op_sel_hi:[1,0,1]
	v_add_u32_e32 v4, 0x2000, v22
	ds_read2_b32 v[36:37], v4 offset1:16
	v_pk_fma_f32 v[6:7], v[26:27], v[32:33], v[6:7] op_sel_hi:[1,0,1]
	s_waitcnt lgkmcnt(0)
	v_pk_fma_f32 v[24:25], v[24:25], v[36:37], v[0:1] op_sel_hi:[1,0,1]
	v_add_co_u32_e32 v0, vcc, s21, v16
	v_pk_fma_f32 v[26:27], v[26:27], v[36:37], v[2:3] op_sel_hi:[1,0,1]
	s_nop 0
	v_addc_co_u32_e32 v1, vcc, 0, v17, vcc
	s_mov_b32 s21, 0x120000
	s_waitcnt vmcnt(14)
	v_mov_b32_e32 v0, v172
	v_mov_b32_e32 v1, v173
	v_mov_b32_e32 v2, v174
	v_mov_b32_e32 v3, v175
	v_pk_fma_f32 v[30:31], v[0:1], v[28:29], v[30:31] op_sel_hi:[1,0,1]
	v_pk_fma_f32 v[10:11], v[2:3], v[28:29], v[10:11] op_sel_hi:[1,0,1]
	v_mov_b32_e32 v28, v33
	v_pk_fma_f32 v[32:33], v[0:1], v[28:29], v[34:35] op_sel_hi:[1,0,1]
	v_pk_fma_f32 v[6:7], v[2:3], v[28:29], v[6:7] op_sel_hi:[1,0,1]
	v_mov_b32_e32 v28, v37
	v_pk_fma_f32 v[24:25], v[0:1], v[28:29], v[24:25] op_sel_hi:[1,0,1]
	v_add_co_u32_e32 v0, vcc, s21, v16
	v_pk_fma_f32 v[26:27], v[2:3], v[28:29], v[26:27] op_sel_hi:[1,0,1]
	s_nop 0
	v_addc_co_u32_e32 v1, vcc, 0, v17, vcc
	ds_read2_b32 v[28:29], v22 offset0:32 offset1:48
	ds_read2_b32 v[34:35], v8 offset0:32 offset1:48
	ds_read2_b32 v[36:37], v4 offset0:32 offset1:48
	s_mov_b32 s21, 0x1b0000
	s_waitcnt vmcnt(13) lgkmcnt(2)
	v_mov_b32_e32 v0, v176
	v_mov_b32_e32 v1, v177
	v_mov_b32_e32 v2, v178
	v_mov_b32_e32 v3, v179
	v_pk_fma_f32 v[30:31], v[0:1], v[28:29], v[30:31] op_sel_hi:[1,0,1]
	s_waitcnt lgkmcnt(1)
	v_pk_fma_f32 v[32:33], v[0:1], v[34:35], v[32:33] op_sel_hi:[1,0,1]
	s_waitcnt lgkmcnt(0)
	v_pk_fma_f32 v[24:25], v[0:1], v[36:37], v[24:25] op_sel_hi:[1,0,1]
	v_add_co_u32_e32 v0, vcc, s21, v16
	v_pk_fma_f32 v[10:11], v[2:3], v[28:29], v[10:11] op_sel_hi:[1,0,1]
	s_nop 0
	v_addc_co_u32_e32 v1, vcc, 0, v17, vcc
	v_pk_fma_f32 v[6:7], v[2:3], v[34:35], v[6:7] op_sel_hi:[1,0,1]
	v_pk_fma_f32 v[26:27], v[2:3], v[36:37], v[26:27] op_sel_hi:[1,0,1]
	v_mov_b32_e32 v28, v29
	s_mov_b32 s21, 0x240000
	s_waitcnt vmcnt(12)
	v_mov_b32_e32 v0, v180
	v_mov_b32_e32 v1, v181
	v_mov_b32_e32 v2, v182
	v_mov_b32_e32 v3, v183
	v_pk_fma_f32 v[30:31], v[0:1], v[28:29], v[30:31] op_sel_hi:[1,0,1]
	v_pk_fma_f32 v[10:11], v[2:3], v[28:29], v[10:11] op_sel_hi:[1,0,1]
	v_mov_b32_e32 v28, v35
	v_pk_fma_f32 v[32:33], v[0:1], v[28:29], v[32:33] op_sel_hi:[1,0,1]
	v_pk_fma_f32 v[6:7], v[2:3], v[28:29], v[6:7] op_sel_hi:[1,0,1]
	v_mov_b32_e32 v28, v37
	v_pk_fma_f32 v[24:25], v[0:1], v[28:29], v[24:25] op_sel_hi:[1,0,1]
	v_add_co_u32_e32 v0, vcc, s21, v16
	v_pk_fma_f32 v[26:27], v[2:3], v[28:29], v[26:27] op_sel_hi:[1,0,1]
	s_nop 0
	v_addc_co_u32_e32 v1, vcc, 0, v17, vcc
	ds_read2_b32 v[28:29], v22 offset0:64 offset1:80
	ds_read2_b32 v[34:35], v8 offset0:64 offset1:80
	ds_read2_b32 v[36:37], v4 offset0:64 offset1:80
	s_mov_b32 s21, 0x2d0000
	s_waitcnt vmcnt(11) lgkmcnt(2)
	v_mov_b32_e32 v0, v184
	v_mov_b32_e32 v1, v185
	v_mov_b32_e32 v2, v186
	v_mov_b32_e32 v3, v187
	v_pk_fma_f32 v[30:31], v[0:1], v[28:29], v[30:31] op_sel_hi:[1,0,1]
	s_waitcnt lgkmcnt(1)
	v_pk_fma_f32 v[32:33], v[0:1], v[34:35], v[32:33] op_sel_hi:[1,0,1]
	s_waitcnt lgkmcnt(0)
	v_pk_fma_f32 v[24:25], v[0:1], v[36:37], v[24:25] op_sel_hi:[1,0,1]
	v_add_co_u32_e32 v0, vcc, s21, v16
	v_pk_fma_f32 v[10:11], v[2:3], v[28:29], v[10:11] op_sel_hi:[1,0,1]
	s_nop 0
	v_addc_co_u32_e32 v1, vcc, 0, v17, vcc
	v_pk_fma_f32 v[6:7], v[2:3], v[34:35], v[6:7] op_sel_hi:[1,0,1]
	v_pk_fma_f32 v[26:27], v[2:3], v[36:37], v[26:27] op_sel_hi:[1,0,1]
	v_mov_b32_e32 v28, v29
	s_mov_b32 s21, 0x360000
	s_waitcnt vmcnt(10)
	v_mov_b32_e32 v0, v188
	v_mov_b32_e32 v1, v189
	v_mov_b32_e32 v2, v190
	v_mov_b32_e32 v3, v191
	v_pk_fma_f32 v[30:31], v[0:1], v[28:29], v[30:31] op_sel_hi:[1,0,1]
	v_pk_fma_f32 v[10:11], v[2:3], v[28:29], v[10:11] op_sel_hi:[1,0,1]
	v_mov_b32_e32 v28, v35
	v_pk_fma_f32 v[32:33], v[0:1], v[28:29], v[32:33] op_sel_hi:[1,0,1]
	v_pk_fma_f32 v[6:7], v[2:3], v[28:29], v[6:7] op_sel_hi:[1,0,1]
	v_mov_b32_e32 v28, v37
	v_pk_fma_f32 v[24:25], v[0:1], v[28:29], v[24:25] op_sel_hi:[1,0,1]
	v_add_co_u32_e32 v0, vcc, s21, v16
	v_pk_fma_f32 v[26:27], v[2:3], v[28:29], v[26:27] op_sel_hi:[1,0,1]
	s_nop 0
	v_addc_co_u32_e32 v1, vcc, 0, v17, vcc
	ds_read2_b32 v[28:29], v22 offset0:96 offset1:112
	ds_read2_b32 v[34:35], v8 offset0:96 offset1:112
	ds_read2_b32 v[36:37], v4 offset0:96 offset1:112
	s_mov_b32 s21, 0x3f0000
	s_waitcnt vmcnt(9) lgkmcnt(2)
	v_mov_b32_e32 v0, v192
	v_mov_b32_e32 v1, v193
	v_mov_b32_e32 v2, v194
	v_mov_b32_e32 v3, v195
	v_pk_fma_f32 v[30:31], v[0:1], v[28:29], v[30:31] op_sel_hi:[1,0,1]
	s_waitcnt lgkmcnt(1)
	v_pk_fma_f32 v[32:33], v[0:1], v[34:35], v[32:33] op_sel_hi:[1,0,1]
	s_waitcnt lgkmcnt(0)
	v_pk_fma_f32 v[24:25], v[0:1], v[36:37], v[24:25] op_sel_hi:[1,0,1]
	v_add_co_u32_e32 v0, vcc, s21, v16
	v_pk_fma_f32 v[10:11], v[2:3], v[28:29], v[10:11] op_sel_hi:[1,0,1]
	s_nop 0
	v_addc_co_u32_e32 v1, vcc, 0, v17, vcc
	v_pk_fma_f32 v[6:7], v[2:3], v[34:35], v[6:7] op_sel_hi:[1,0,1]
	v_pk_fma_f32 v[26:27], v[2:3], v[36:37], v[26:27] op_sel_hi:[1,0,1]
	v_mov_b32_e32 v28, v29
	s_mov_b32 s21, 0x480000
	s_waitcnt vmcnt(8)
	v_mov_b32_e32 v0, v196
	v_mov_b32_e32 v1, v197
	v_mov_b32_e32 v2, v198
	v_mov_b32_e32 v3, v199
	v_pk_fma_f32 v[30:31], v[0:1], v[28:29], v[30:31] op_sel_hi:[1,0,1]
	v_pk_fma_f32 v[10:11], v[2:3], v[28:29], v[10:11] op_sel_hi:[1,0,1]
	v_mov_b32_e32 v28, v35
	v_pk_fma_f32 v[32:33], v[0:1], v[28:29], v[32:33] op_sel_hi:[1,0,1]
	v_pk_fma_f32 v[6:7], v[2:3], v[28:29], v[6:7] op_sel_hi:[1,0,1]
	v_mov_b32_e32 v28, v37
	v_pk_fma_f32 v[24:25], v[0:1], v[28:29], v[24:25] op_sel_hi:[1,0,1]
	v_add_co_u32_e32 v0, vcc, s21, v16
	v_pk_fma_f32 v[26:27], v[2:3], v[28:29], v[26:27] op_sel_hi:[1,0,1]
	s_nop 0
	v_addc_co_u32_e32 v1, vcc, 0, v17, vcc
	ds_read2_b32 v[28:29], v22 offset0:128 offset1:144
	ds_read2_b32 v[34:35], v8 offset0:128 offset1:144
	ds_read2_b32 v[36:37], v4 offset0:128 offset1:144
	s_mov_b32 s21, 0x510000
	s_waitcnt vmcnt(7) lgkmcnt(2)
	v_mov_b32_e32 v0, v200
	v_mov_b32_e32 v1, v201
	v_mov_b32_e32 v2, v202
	v_mov_b32_e32 v3, v203
	v_pk_fma_f32 v[30:31], v[0:1], v[28:29], v[30:31] op_sel_hi:[1,0,1]
	s_waitcnt lgkmcnt(1)
	v_pk_fma_f32 v[32:33], v[0:1], v[34:35], v[32:33] op_sel_hi:[1,0,1]
	s_waitcnt lgkmcnt(0)
	v_pk_fma_f32 v[24:25], v[0:1], v[36:37], v[24:25] op_sel_hi:[1,0,1]
	v_add_co_u32_e32 v0, vcc, s21, v16
	v_pk_fma_f32 v[10:11], v[2:3], v[28:29], v[10:11] op_sel_hi:[1,0,1]
	s_nop 0
	v_addc_co_u32_e32 v1, vcc, 0, v17, vcc
	v_pk_fma_f32 v[6:7], v[2:3], v[34:35], v[6:7] op_sel_hi:[1,0,1]
	v_pk_fma_f32 v[26:27], v[2:3], v[36:37], v[26:27] op_sel_hi:[1,0,1]
	v_mov_b32_e32 v28, v29
	s_mov_b32 s21, 0x5a0000
	s_waitcnt vmcnt(6)
	v_mov_b32_e32 v0, v204
	v_mov_b32_e32 v1, v205
	v_mov_b32_e32 v2, v206
	v_mov_b32_e32 v3, v207
	v_pk_fma_f32 v[30:31], v[0:1], v[28:29], v[30:31] op_sel_hi:[1,0,1]
	v_pk_fma_f32 v[10:11], v[2:3], v[28:29], v[10:11] op_sel_hi:[1,0,1]
	v_mov_b32_e32 v28, v35
	v_pk_fma_f32 v[32:33], v[0:1], v[28:29], v[32:33] op_sel_hi:[1,0,1]
	v_pk_fma_f32 v[6:7], v[2:3], v[28:29], v[6:7] op_sel_hi:[1,0,1]
	v_mov_b32_e32 v28, v37
	v_pk_fma_f32 v[24:25], v[0:1], v[28:29], v[24:25] op_sel_hi:[1,0,1]
	v_add_co_u32_e32 v0, vcc, s21, v16
	v_pk_fma_f32 v[26:27], v[2:3], v[28:29], v[26:27] op_sel_hi:[1,0,1]
	s_nop 0
	v_addc_co_u32_e32 v1, vcc, 0, v17, vcc
	ds_read2_b32 v[28:29], v22 offset0:160 offset1:176
	ds_read2_b32 v[34:35], v8 offset0:160 offset1:176
	ds_read2_b32 v[36:37], v4 offset0:160 offset1:176
	s_mov_b32 s21, 0x630000
	s_waitcnt vmcnt(5) lgkmcnt(2)
	v_mov_b32_e32 v0, v208
	v_mov_b32_e32 v1, v209
	v_mov_b32_e32 v2, v210
	v_mov_b32_e32 v3, v211
	v_pk_fma_f32 v[30:31], v[0:1], v[28:29], v[30:31] op_sel_hi:[1,0,1]
	s_waitcnt lgkmcnt(1)
	v_pk_fma_f32 v[32:33], v[0:1], v[34:35], v[32:33] op_sel_hi:[1,0,1]
	s_waitcnt lgkmcnt(0)
	v_pk_fma_f32 v[24:25], v[0:1], v[36:37], v[24:25] op_sel_hi:[1,0,1]
	v_add_co_u32_e32 v0, vcc, s21, v16
	v_pk_fma_f32 v[10:11], v[2:3], v[28:29], v[10:11] op_sel_hi:[1,0,1]
	s_nop 0
	v_addc_co_u32_e32 v1, vcc, 0, v17, vcc
	v_pk_fma_f32 v[6:7], v[2:3], v[34:35], v[6:7] op_sel_hi:[1,0,1]
	v_pk_fma_f32 v[26:27], v[2:3], v[36:37], v[26:27] op_sel_hi:[1,0,1]
	v_mov_b32_e32 v28, v29
	s_mov_b32 s21, 0x6c0000
	s_waitcnt vmcnt(4)
	v_mov_b32_e32 v0, v212
	v_mov_b32_e32 v1, v213
	v_mov_b32_e32 v2, v214
	v_mov_b32_e32 v3, v215
	v_pk_fma_f32 v[30:31], v[0:1], v[28:29], v[30:31] op_sel_hi:[1,0,1]
	v_pk_fma_f32 v[10:11], v[2:3], v[28:29], v[10:11] op_sel_hi:[1,0,1]
	v_mov_b32_e32 v28, v35
	v_pk_fma_f32 v[32:33], v[0:1], v[28:29], v[32:33] op_sel_hi:[1,0,1]
	v_pk_fma_f32 v[6:7], v[2:3], v[28:29], v[6:7] op_sel_hi:[1,0,1]
	v_mov_b32_e32 v28, v37
	v_pk_fma_f32 v[24:25], v[0:1], v[28:29], v[24:25] op_sel_hi:[1,0,1]
	v_add_co_u32_e32 v0, vcc, s21, v16
	v_pk_fma_f32 v[26:27], v[2:3], v[28:29], v[26:27] op_sel_hi:[1,0,1]
	s_nop 0
	v_addc_co_u32_e32 v1, vcc, 0, v17, vcc
	ds_read2_b32 v[28:29], v22 offset0:192 offset1:208
	ds_read2_b32 v[34:35], v8 offset0:192 offset1:208
	ds_read2_b32 v[36:37], v4 offset0:192 offset1:208
	s_mov_b32 s21, 0x750000
	s_waitcnt vmcnt(3) lgkmcnt(2)
	v_mov_b32_e32 v0, v216
	v_mov_b32_e32 v1, v217
	v_mov_b32_e32 v2, v218
	v_mov_b32_e32 v3, v219
	v_pk_fma_f32 v[30:31], v[0:1], v[28:29], v[30:31] op_sel_hi:[1,0,1]
	s_waitcnt lgkmcnt(1)
	v_pk_fma_f32 v[32:33], v[0:1], v[34:35], v[32:33] op_sel_hi:[1,0,1]
	s_waitcnt lgkmcnt(0)
	v_pk_fma_f32 v[24:25], v[0:1], v[36:37], v[24:25] op_sel_hi:[1,0,1]
	v_add_co_u32_e32 v0, vcc, s21, v16
	v_pk_fma_f32 v[10:11], v[2:3], v[28:29], v[10:11] op_sel_hi:[1,0,1]
	s_nop 0
	v_addc_co_u32_e32 v1, vcc, 0, v17, vcc
	v_pk_fma_f32 v[6:7], v[2:3], v[34:35], v[6:7] op_sel_hi:[1,0,1]
	v_pk_fma_f32 v[26:27], v[2:3], v[36:37], v[26:27] op_sel_hi:[1,0,1]
	v_mov_b32_e32 v28, v29
	s_mov_b32 s21, 0x7e0000
	s_waitcnt vmcnt(2)
	v_mov_b32_e32 v0, v220
	v_mov_b32_e32 v1, v221
	v_mov_b32_e32 v2, v222
	v_mov_b32_e32 v3, v223
	v_pk_fma_f32 v[30:31], v[0:1], v[28:29], v[30:31] op_sel_hi:[1,0,1]
	v_pk_fma_f32 v[10:11], v[2:3], v[28:29], v[10:11] op_sel_hi:[1,0,1]
	v_mov_b32_e32 v28, v35
	v_pk_fma_f32 v[32:33], v[0:1], v[28:29], v[32:33] op_sel_hi:[1,0,1]
	v_pk_fma_f32 v[6:7], v[2:3], v[28:29], v[6:7] op_sel_hi:[1,0,1]
	v_mov_b32_e32 v28, v37
	v_pk_fma_f32 v[24:25], v[0:1], v[28:29], v[24:25] op_sel_hi:[1,0,1]
	v_add_co_u32_e32 v0, vcc, s21, v16
	v_pk_fma_f32 v[26:27], v[2:3], v[28:29], v[26:27] op_sel_hi:[1,0,1]
	s_nop 0
	v_addc_co_u32_e32 v1, vcc, 0, v17, vcc
	ds_read2_b32 v[28:29], v22 offset0:224 offset1:240
	ds_read2_b32 v[34:35], v8 offset0:224 offset1:240
	ds_read2_b32 v[36:37], v4 offset0:224 offset1:240
	s_mov_b32 s21, 0x870000
	v_add_u32_e32 v22, 0x400, v22
	s_waitcnt lgkmcnt(2)
	v_mov_b32_e32 v4, v29
	s_waitcnt vmcnt(1)
	v_mov_b32_e32 v0, v224
	v_mov_b32_e32 v1, v225
	v_mov_b32_e32 v2, v226
	v_mov_b32_e32 v3, v227
	v_pk_fma_f32 v[30:31], v[0:1], v[28:29], v[30:31] op_sel_hi:[1,0,1]
	s_waitcnt lgkmcnt(1)
	v_pk_fma_f32 v[32:33], v[0:1], v[34:35], v[32:33] op_sel_hi:[1,0,1]
	s_waitcnt lgkmcnt(0)
	v_pk_fma_f32 v[24:25], v[0:1], v[36:37], v[24:25] op_sel_hi:[1,0,1]
	v_add_co_u32_e32 v0, vcc, s21, v16
	v_pk_fma_f32 v[10:11], v[2:3], v[28:29], v[10:11] op_sel_hi:[1,0,1]
	s_nop 0
	v_addc_co_u32_e32 v1, vcc, 0, v17, vcc
	v_pk_fma_f32 v[6:7], v[2:3], v[34:35], v[6:7] op_sel_hi:[1,0,1]
	v_pk_fma_f32 v[26:27], v[2:3], v[36:37], v[26:27] op_sel_hi:[1,0,1]
	v_mov_b32_e32 v16, v35
	s_waitcnt vmcnt(0)
	v_mov_b32_e32 v0, v228
	v_mov_b32_e32 v1, v229
	v_mov_b32_e32 v2, v230
	v_mov_b32_e32 v3, v231
	v_pk_fma_f32 v[8:9], v[0:1], v[4:5], v[30:31] op_sel_hi:[1,0,1]
	v_pk_fma_f32 v[10:11], v[2:3], v[4:5], v[10:11] op_sel_hi:[1,0,1]
	v_pk_fma_f32 v[4:5], v[0:1], v[16:17], v[32:33] op_sel_hi:[1,0,1]
	v_pk_fma_f32 v[6:7], v[2:3], v[16:17], v[6:7] op_sel_hi:[1,0,1]
	v_mov_b32_e32 v16, v37
	v_pk_fma_f32 v[0:1], v[0:1], v[16:17], v[24:25] op_sel_hi:[1,0,1]
	v_pk_fma_f32 v[2:3], v[2:3], v[16:17], v[26:27] op_sel_hi:[1,0,1]
	s_cbranch_scc0 .LBB0_66
	s_movk_i32 s21, 0x300
	v_and_b32_e32 v14, 60, v21
	v_mul_lo_u32 v12, v12, s21
	s_movk_i32 s21, 0xc0
	v_lshl_or_b32 v12, v14, 2, v12
	v_cmp_gt_i32_e32 vcc, s21, v20
	ds_write_b128 v12, v[8:11] offset:12288
	ds_write_b128 v12, v[4:7] offset:12544
	ds_write_b128 v12, v[0:3] offset:12800
	s_waitcnt lgkmcnt(0)
	s_barrier
	s_and_saveexec_b64 s[22:23], vcc
	s_cbranch_execz .LBB0_24
	v_ashrrev_i32_e32 v1, 6, v20
	v_and_b32_e32 v4, 63, v20
	v_lshlrev_b32_e32 v0, 8, v1
	v_lshl_or_b32 v0, v4, 2, v0
	ds_read2st64_b32 v[2:3], v0 offset0:48 offset1:51
	s_ashr_i32 s38, s24, 4
	s_mul_hi_i32 s34, s38, 0x55555556
	v_readlane_b32 s4, v164, 17
	v_readlane_b32 s5, v164, 18
	s_waitcnt lgkmcnt(0)
	v_add_f32_e32 v2, 0, v2
	v_add_f32_e32 v5, v2, v3
	ds_read2st64_b32 v[2:3], v0 offset0:54 offset1:57
	s_mov_b64 s[24:25], -1
	s_mul_i32 s36, s0, 3
	s_mov_b64 s[26:27], 0
	v_readlane_b32 s6, v164, 19
	s_waitcnt lgkmcnt(0)
	v_add_f32_e32 v2, v5, v2
	v_add_f32_e32 v5, v2, v3
	ds_read2st64_b32 v[2:3], v0 offset0:60 offset1:63
	v_readlane_b32 s7, v164, 20
	v_readlane_b32 s8, v164, 21
	v_readlane_b32 s9, v164, 22
	v_readlane_b32 s10, v164, 23
	s_waitcnt lgkmcnt(0)
	v_add_f32_e32 v2, v5, v2
	v_add_f32_e32 v5, v2, v3
	ds_read2st64_b32 v[2:3], v0 offset0:66 offset1:69
	v_readlane_b32 s11, v164, 24
	v_readlane_b32 s12, v164, 25
	v_readlane_b32 s13, v164, 26
	v_readlane_b32 s14, v164, 27
	s_waitcnt lgkmcnt(0)
	v_add_f32_e32 v2, v5, v2
	v_add_f32_e32 v5, v2, v3
	ds_read2st64_b32 v[2:3], v0 offset0:72 offset1:75
	v_readlane_b32 s15, v164, 28
	v_readlane_b32 s16, v164, 29
	v_readlane_b32 s17, v164, 30
	v_readlane_b32 s18, v164, 31
	s_waitcnt lgkmcnt(0)
	v_add_f32_e32 v2, v5, v2
	v_add_f32_e32 v5, v2, v3
	ds_read2st64_b32 v[2:3], v0 offset0:78 offset1:81
	v_readlane_b32 s19, v164, 32
	s_waitcnt lgkmcnt(0)
	v_add_f32_e32 v2, v5, v2
	v_add_f32_e32 v5, v2, v3
	ds_read2st64_b32 v[2:3], v0 offset0:84 offset1:87
	s_waitcnt lgkmcnt(0)
	v_add_f32_e32 v2, v5, v2
	v_add_f32_e32 v5, v2, v3
	ds_read2st64_b32 v[2:3], v0 offset0:90 offset1:93
	s_waitcnt lgkmcnt(0)
	v_add_f32_e32 v0, v5, v2
	v_add_f32_e32 v3, v0, v3
	v_or_b32_e32 v0, s20, v4
	v_mov_b32_e32 v2, s20
	s_lshr_b32 s20, s34, 31
	s_add_i32 s34, s34, s20
	s_mul_i32 s20, s0, 0x2400
	v_bitop3_b32 v2, v4, s30, v2 bitop3:0xc8
	v_add_u32_e32 v4, s20, v0
	v_ashrrev_i32_e32 v5, 31, v4
	v_lshl_add_u64 v[4:5], v[4:5], 2, s[4:5]
	global_load_dword v4, v[4:5], off
	s_mul_i32 s35, s34, -3
	s_add_i32 s35, s35, s38
	s_mov_b64 s[20:21], 0
	s_cmp_lt_i32 s35, 2
	s_waitcnt vmcnt(0)
	v_add_f32_e32 v3, v3, v4
	s_cbranch_scc0 .LBB0_73
	s_and_b64 vcc, exec, s[24:25]
	s_cbranch_vccnz .LBB0_76

.LBB0_185:
	s_mul_i32 s0, s47, s46
	s_mul_i32 s0, s0, s33
	s_lshr_b32 s2, s46, 3
	v_writelane_b32 v163, s0, 19
	s_add_u32 s0, s84, 0x200
	s_addc_u32 s1, s85, 0
	v_writelane_b32 v163, s0, 20
	s_mov_b32 s37, 0
	v_mbcnt_lo_u32_b32 v0, -1, 0
	v_writelane_b32 v163, s1, 21
	s_add_u32 s0, s84, 0x1000
	s_addc_u32 s1, s85, 0
	v_writelane_b32 v163, s0, 22
	v_mov_b32_e32 v117, 0
	v_mov_b32_e32 v129, 1
	v_writelane_b32 v163, s1, 23
	s_add_u32 s0, s84, 0x1100
	s_addc_u32 s1, s85, 0
	v_writelane_b32 v163, s0, 24
	v_mov_b32_e32 v130, 0x358637bd
	v_mov_b32_e32 v131, 0x3ca908c9
	v_writelane_b32 v163, s1, 25
	s_add_u32 s0, s84, 0x1200
	s_addc_u32 s1, s85, 0
	v_writelane_b32 v163, s0, 26
	v_mov_b32_e32 v132, 0x3a27c5ac
	v_mbcnt_hi_u32_b32 v133, -1, v0
	v_writelane_b32 v163, s1, 27
	s_add_u32 s0, s84, 0x1300
	s_addc_u32 s1, s85, 0
	v_writelane_b32 v163, s0, 28
	s_cmp_eq_u32 s40, 15
	v_mov_b32_e32 v134, 0x7f800000
	v_writelane_b32 v163, s1, 29
	s_cselect_b64 s[0:1], -1, 0
	v_writelane_b32 v163, s0, 30
	s_cmp_eq_u32 s40, 14
	v_mov_b32_e32 v135, 0xc800
	v_writelane_b32 v163, s1, 31
	s_cselect_b64 s[0:1], -1, 0
	v_writelane_b32 v163, s0, 32
	s_cmp_eq_u32 s40, 13
	v_mov_b32_e32 v136, 0xf149f2ca
	v_writelane_b32 v163, s1, 33
	s_cselect_b64 s[0:1], -1, 0
	v_writelane_b32 v163, s0, 34
	s_cmp_eq_u32 s40, 12
	v_mov_b32_e32 v137, 0xb00
	v_writelane_b32 v163, s1, 35
	s_cselect_b64 s[0:1], -1, 0
	v_writelane_b32 v163, s0, 36
	s_cmp_eq_u32 s40, 11
	v_mov_b32_e32 v138, 0x600
	v_writelane_b32 v163, s1, 37
	s_cselect_b64 s[0:1], -1, 0
	v_writelane_b32 v163, s0, 38
	s_cmp_eq_u32 s40, 10
	v_mov_b32_e32 v139, 0xb00000
	v_writelane_b32 v163, s1, 39
	s_cselect_b64 s[0:1], -1, 0
	v_writelane_b32 v163, s0, 40
	s_cmp_eq_u32 s40, 9
	s_mov_b32 s29, 0x10000
	v_writelane_b32 v163, s1, 41
	s_cselect_b64 s[0:1], -1, 0
	v_writelane_b32 v163, s0, 42
	s_cmp_eq_u32 s40, 8
	s_mov_b32 s28, 0x20000
	v_writelane_b32 v163, s1, 43
	s_cselect_b64 s[0:1], -1, 0
	v_writelane_b32 v163, s0, 44
	s_cmp_eq_u32 s40, 7
	s_mov_b32 s27, 0x30000
	v_writelane_b32 v163, s1, 45
	s_cselect_b64 s[0:1], -1, 0
	v_writelane_b32 v163, s0, 46
	s_cmp_eq_u32 s40, 6
	s_movk_i32 s96, 0x2000
	v_writelane_b32 v163, s1, 47
	s_cselect_b64 s[0:1], -1, 0
	v_writelane_b32 v163, s0, 48
	s_cmp_eq_u32 s40, 5
	s_mov_b32 s97, 0x12000
	v_writelane_b32 v163, s1, 49
	s_cselect_b64 s[0:1], -1, 0
	v_writelane_b32 v163, s0, 50
	s_cmp_eq_u32 s40, 4
	s_movk_i32 s88, 0x7fff
	v_writelane_b32 v163, s1, 51
	s_cselect_b64 s[0:1], -1, 0
	v_writelane_b32 v163, s0, 52
	s_cmp_eq_u32 s40, 3
	s_mov_b32 s91, 0x84000
	v_writelane_b32 v163, s1, 53
	s_cselect_b64 s[0:1], -1, 0
	v_writelane_b32 v163, s0, 54
	s_cmp_eq_u32 s40, 2
	s_mov_b32 s89, 0x58000
	v_writelane_b32 v163, s1, 55
	s_cselect_b64 s[0:1], -1, 0
	v_writelane_b32 v163, s0, 56
	s_cmp_eq_u32 s40, 1
	s_mov_b32 s92, 0x2c000
	v_writelane_b32 v163, s1, 57
	s_cselect_b64 s[0:1], -1, 0
	v_writelane_b32 v163, s0, 58
	s_cmp_eq_u32 s40, 0
	s_movk_i32 s33, 0x2f00
	v_writelane_b32 v163, s1, 59
	s_cselect_b64 s[0:1], -1, 0
	v_writelane_b32 v163, s0, 60
	s_movk_i32 s26, 0x1400
	s_mov_b32 s93, 0x8000
	v_writelane_b32 v163, s1, 61
	s_lshl_b32 s0, s40, 8
	s_add_u32 s0, s84, s0
	s_addc_u32 s1, s85, 0
	s_add_u32 s4, s0, 0x1400
	s_addc_u32 s5, s1, 0
	s_add_u32 s0, s0, 0x2400
	s_addc_u32 s1, s1, 0
	v_writelane_b32 v162, s0, 0
	v_writelane_b32 v163, s4, 62
	s_mov_b32 s90, 0x3e000000
	v_writelane_b32 v162, s1, 1
	s_add_u32 s0, s84, 0x3400
	s_addc_u32 s1, s85, 0
	v_writelane_b32 v162, s0, 2
	v_writelane_b32 v163, s5, 63
	s_mov_b64 s[30:31], 0x800
	v_writelane_b32 v162, s1, 3
	s_add_u32 s0, s84, 0x3500
	s_addc_u32 s1, s85, 0
	v_writelane_b32 v162, s0, 4
	s_cmpk_lg_i32 s2, 0x60
	s_nop 0
	v_writelane_b32 v162, s1, 5
	s_cselect_b64 s[0:1], -1, 0
	v_writelane_b32 v162, s0, 6
	s_nop 1
	v_writelane_b32 v162, s1, 7
	s_lshl_b32 s0, s46, 4
	v_writelane_b32 v162, s0, 8
	s_add_u32 s0, s84, 0x3600
	v_writelane_b32 v162, s0, 9
	s_addc_u32 s0, s85, 0
	v_writelane_b32 v162, s0, 10
	s_lshl_b32 s0, s2, 7
	v_writelane_b32 v162, s0, 11
	v_writelane_b32 v162, s44, 12
	s_and_b32 s0, s46, -8
	s_ashr_i32 s35, s34, 31
	v_writelane_b32 v162, s45, 13
	v_writelane_b32 v162, s46, 14
	v_writelane_b32 v162, s47, 15
	v_writelane_b32 v162, s0, 16
	v_writelane_b32 v162, s2, 17
	s_lshl_b32 s0, s2, 4
	v_writelane_b32 v162, s0, 18
	v_readlane_b32 s0, v164, 33
	s_lshl_b64 s[94:95], s[34:35], 11
	v_readlane_b32 s14, v164, 47
	v_readlane_b32 s1, v164, 34
	v_readlane_b32 s15, v164, 48
	s_add_u32 s0, s14, 0x408
	s_addc_u32 s1, s15, 0
	v_readlane_b32 s10, v164, 43
	v_writelane_b32 v162, s0, 19
	v_readlane_b32 s11, v164, 44
	v_readlane_b32 s2, v164, 35
	v_writelane_b32 v162, s1, 20
	s_add_u32 s0, s10, 0x408
	s_addc_u32 s1, s11, 0
	v_readlane_b32 s3, v164, 36
	v_readlane_b32 s4, v164, 37
	v_readlane_b32 s5, v164, 38
	v_readlane_b32 s6, v164, 39
	v_readlane_b32 s7, v164, 40
	v_readlane_b32 s8, v164, 41
	v_readlane_b32 s9, v164, 42
	v_readlane_b32 s12, v164, 45
	v_readlane_b32 s13, v164, 46
	v_writelane_b32 v162, s0, 21
	s_nop 1
	v_writelane_b32 v162, s1, 22
	v_readlane_b32 s0, v164, 49
	v_readlane_b32 s1, v164, 50
	s_add_u32 s0, s0, 0x800
	v_writelane_b32 v162, s0, 23
	s_addc_u32 s0, s1, 0
	v_readlane_b32 s2, v164, 51
	v_writelane_b32 v162, s0, 24
	s_movk_i32 s0, 0xc38
	v_readlane_b32 s3, v164, 52
	v_writelane_b32 v162, s0, 25
	s_mov_b32 s2, s34
	v_writelane_b32 v162, s2, 26
	s_mov_b64 s[0:1], 0x1000
	v_readlane_b32 s4, v164, 53
	v_writelane_b32 v162, s3, 27
	s_lshl_b64 s[2:3], s[34:35], 12
	v_writelane_b32 v162, s2, 28
	s_mov_b32 s34, s37
	v_readlane_b32 s5, v164, 54
	v_writelane_b32 v162, s3, 29
	s_mov_b64 s[2:3], -1
	v_writelane_b32 v162, s2, 30
	v_readlane_b32 s6, v164, 55
	v_readlane_b32 s7, v164, 56
	v_writelane_b32 v162, s3, 31
	v_writelane_b32 v162, s68, 32
	v_readlane_b32 s8, v164, 57
	v_readlane_b32 s9, v164, 58
	v_writelane_b32 v162, s69, 33
	v_writelane_b32 v162, s70, 34
	v_readlane_b32 s10, v164, 59
	v_readlane_b32 s11, v164, 60
	v_readlane_b32 s12, v164, 61
	v_readlane_b32 s13, v164, 62
	v_readlane_b32 s14, v164, 63
	v_readlane_b32 s15, v163, 0
	v_writelane_b32 v162, s71, 35
	s_branch .LBB0_189

.Lggu0_pair:
	s_waitcnt vmcnt(0)
	s_barrier
	ds_read_b128 v[80:83], v204 offset:0
	ds_read_b128 v[100:103], v206 offset:20480
	ds_read_b128 v[104:107], v206 offset:22528
	ds_read_b128 v[108:111], v206 offset:24576
	ds_read_b128 v[112:115], v206 offset:26624
	ds_read_b128 v[84:87], v204 offset:2048
	ds_read_b128 v[88:91], v204 offset:4096
	ds_read_b128 v[92:95], v204 offset:6144
	ds_read_b128 v[96:99], v204 offset:8192
	s_add_u32 m0, s13, 0xd100
	s_waitcnt lgkmcnt(7)
	v_mfma_f32_16x16x32_bf16 v[0:3], v[100:103], v[80:83], v[0:3]
	global_load_lds_dwordx4 v208, s[2:3]
	s_add_u32 m0, s13, 0xe100
	s_waitcnt lgkmcnt(6)
	v_mfma_f32_16x16x32_bf16 v[4:7], v[104:107], v[80:83], v[4:7]
	global_load_lds_dwordx4 v209, s[2:3]
	s_add_u32 m0, s13, 0xf100
	s_waitcnt lgkmcnt(5)
	v_mfma_f32_16x16x32_bf16 v[8:11], v[108:111], v[80:83], v[8:11]
	global_load_lds_dwordx4 v210, s[2:3]
	s_add_u32 m0, s13, 0x10100
	s_waitcnt lgkmcnt(4)
	v_mfma_f32_16x16x32_bf16 v[12:15], v[112:115], v[80:83], v[12:15]
	global_load_lds_dwordx4 v211, s[2:3]
	s_add_u32 m0, s13, 0x11100
	ds_read_b128 v[168:171], v205 offset:0
	ds_read_b128 v[188:191], v207 offset:20480
	ds_read_b128 v[192:195], v207 offset:22528
	ds_read_b128 v[196:199], v207 offset:24576
	ds_read_b128 v[200:203], v207 offset:26624
	s_waitcnt lgkmcnt(8)
	v_mfma_f32_16x16x32_bf16 v[16:19], v[100:103], v[84:87], v[16:19]
	global_load_lds_dwordx4 v212, s[2:3]
	s_add_u32 m0, s13, 0x9000
	v_mfma_f32_16x16x32_bf16 v[20:23], v[104:107], v[84:87], v[20:23]
	global_load_lds_dwordx4 v213, s[6:7]
	s_add_u32 m0, s13, 0xa000
	v_mfma_f32_16x16x32_bf16 v[24:27], v[108:111], v[84:87], v[24:27]
	global_load_lds_dwordx4 v214, s[6:7]
	s_add_u32 m0, s13, 0xb000
	v_mfma_f32_16x16x32_bf16 v[28:31], v[112:115], v[84:87], v[28:31]
	global_load_lds_dwordx4 v215, s[6:7]
	s_add_u32 m0, s13, 0xc000
	ds_read_b128 v[172:175], v205 offset:2048
	ds_read_b128 v[176:179], v205 offset:4096
	ds_read_b128 v[180:183], v205 offset:6144
	ds_read_b128 v[184:187], v205 offset:8192
	s_waitcnt lgkmcnt(11)
	v_mfma_f32_16x16x32_bf16 v[32:35], v[100:103], v[88:91], v[32:35]
	global_load_lds_dwordx4 v216, s[6:7]
	v_mfma_f32_16x16x32_bf16 v[36:39], v[104:107], v[88:91], v[36:39]
	v_mfma_f32_16x16x32_bf16 v[40:43], v[108:111], v[88:91], v[40:43]
	v_mfma_f32_16x16x32_bf16 v[44:47], v[112:115], v[88:91], v[44:47]
	s_waitcnt lgkmcnt(10)
	v_mfma_f32_16x16x32_bf16 v[48:51], v[100:103], v[92:95], v[48:51]
	v_mfma_f32_16x16x32_bf16 v[52:55], v[104:107], v[92:95], v[52:55]
	v_mfma_f32_16x16x32_bf16 v[56:59], v[108:111], v[92:95], v[56:59]
	v_mfma_f32_16x16x32_bf16 v[60:63], v[112:115], v[92:95], v[60:63]
	s_waitcnt lgkmcnt(9)
	v_mfma_f32_16x16x32_bf16 v[64:67], v[100:103], v[96:99], v[64:67]
	v_mfma_f32_16x16x32_bf16 v[68:71], v[104:107], v[96:99], v[68:71]
	v_mfma_f32_16x16x32_bf16 v[72:75], v[108:111], v[96:99], v[72:75]
	v_mfma_f32_16x16x32_bf16 v[76:79], v[112:115], v[96:99], v[76:79]
	s_waitcnt lgkmcnt(7)
	v_mfma_f32_16x16x32_bf16 v[0:3], v[188:191], v[168:171], v[0:3]
	s_waitcnt lgkmcnt(6)
	v_mfma_f32_16x16x32_bf16 v[4:7], v[192:195], v[168:171], v[4:7]
	s_waitcnt lgkmcnt(5)
	v_mfma_f32_16x16x32_bf16 v[8:11], v[196:199], v[168:171], v[8:11]
	s_waitcnt lgkmcnt(4)
	v_mfma_f32_16x16x32_bf16 v[12:15], v[200:203], v[168:171], v[12:15]
	s_waitcnt lgkmcnt(3)
	v_mfma_f32_16x16x32_bf16 v[16:19], v[188:191], v[172:175], v[16:19]
	v_mfma_f32_16x16x32_bf16 v[20:23], v[192:195], v[172:175], v[20:23]
	v_mfma_f32_16x16x32_bf16 v[24:27], v[196:199], v[172:175], v[24:27]
	v_mfma_f32_16x16x32_bf16 v[28:31], v[200:203], v[172:175], v[28:31]
	s_waitcnt lgkmcnt(2)
	v_mfma_f32_16x16x32_bf16 v[32:35], v[188:191], v[176:179], v[32:35]
	v_mfma_f32_16x16x32_bf16 v[36:39], v[192:195], v[176:179], v[36:39]
	v_mfma_f32_16x16x32_bf16 v[40:43], v[196:199], v[176:179], v[40:43]
	v_mfma_f32_16x16x32_bf16 v[44:47], v[200:203], v[176:179], v[44:47]
	s_waitcnt lgkmcnt(1)
	v_mfma_f32_16x16x32_bf16 v[48:51], v[188:191], v[180:183], v[48:51]
	v_mfma_f32_16x16x32_bf16 v[52:55], v[192:195], v[180:183], v[52:55]
	v_mfma_f32_16x16x32_bf16 v[56:59], v[196:199], v[180:183], v[56:59]
	v_mfma_f32_16x16x32_bf16 v[60:63], v[200:203], v[180:183], v[60:63]
	s_add_u32 s2, s2, 0x80
	s_addc_u32 s3, s3, 0
	s_add_u32 s6, s6, 0x80
	s_addc_u32 s7, s7, 0
	s_waitcnt lgkmcnt(0)
	v_mfma_f32_16x16x32_bf16 v[64:67], v[188:191], v[184:187], v[64:67]
	v_mfma_f32_16x16x32_bf16 v[68:71], v[192:195], v[184:187], v[68:71]
	v_mfma_f32_16x16x32_bf16 v[72:75], v[196:199], v[184:187], v[72:75]
	v_mfma_f32_16x16x32_bf16 v[76:79], v[200:203], v[184:187], v[76:79]
	s_cmp_eq_u32 s12, 1
	s_cselect_b32 s2, s20, s2
	s_cselect_b32 s3, s21, s3
	s_cselect_b32 s6, s22, s6
	s_cselect_b32 s7, s23, s7
	s_waitcnt vmcnt(0)
	s_barrier
	ds_read_b128 v[80:83], v204 offset:53504
	ds_read_b128 v[100:103], v206 offset:36864
	ds_read_b128 v[104:107], v206 offset:38912
	ds_read_b128 v[108:111], v206 offset:40960
	ds_read_b128 v[112:115], v206 offset:43008
	ds_read_b128 v[84:87], v204 offset:55552
	ds_read_b128 v[88:91], v204 offset:57600
	ds_read_b128 v[92:95], v204 offset:59648
	ds_read_b128 v[96:99], v204 offset:61696
	s_add_u32 m0, s13, 0x0
	s_waitcnt lgkmcnt(7)
	v_mfma_f32_16x16x32_bf16 v[0:3], v[100:103], v[80:83], v[0:3]
	global_load_lds_dwordx4 v208, s[2:3]
	s_add_u32 m0, s13, 0x1000
	s_waitcnt lgkmcnt(6)
	v_mfma_f32_16x16x32_bf16 v[4:7], v[104:107], v[80:83], v[4:7]
	global_load_lds_dwordx4 v209, s[2:3]
	s_add_u32 m0, s13, 0x2000
	s_waitcnt lgkmcnt(5)
	v_mfma_f32_16x16x32_bf16 v[8:11], v[108:111], v[80:83], v[8:11]
	global_load_lds_dwordx4 v210, s[2:3]
	s_add_u32 m0, s13, 0x3000
	s_waitcnt lgkmcnt(4)
	v_mfma_f32_16x16x32_bf16 v[12:15], v[112:115], v[80:83], v[12:15]
	global_load_lds_dwordx4 v211, s[2:3]
	s_add_u32 m0, s13, 0x4000
	ds_read_b128 v[168:171], v205 offset:53504
	ds_read_b128 v[188:191], v207 offset:36864
	ds_read_b128 v[192:195], v207 offset:38912
	ds_read_b128 v[196:199], v207 offset:40960
	ds_read_b128 v[200:203], v207 offset:43008
	s_waitcnt lgkmcnt(8)
	v_mfma_f32_16x16x32_bf16 v[16:19], v[100:103], v[84:87], v[16:19]
	global_load_lds_dwordx4 v212, s[2:3]
	s_add_u32 m0, s13, 0x5000
	v_mfma_f32_16x16x32_bf16 v[20:23], v[104:107], v[84:87], v[20:23]
	global_load_lds_dwordx4 v213, s[6:7]
	s_add_u32 m0, s13, 0x6000
	v_mfma_f32_16x16x32_bf16 v[24:27], v[108:111], v[84:87], v[24:27]
	global_load_lds_dwordx4 v214, s[6:7]
	s_add_u32 m0, s13, 0x7000
	v_mfma_f32_16x16x32_bf16 v[28:31], v[112:115], v[84:87], v[28:31]
	global_load_lds_dwordx4 v215, s[6:7]
	s_add_u32 m0, s13, 0x8000
	ds_read_b128 v[172:175], v205 offset:55552
	ds_read_b128 v[176:179], v205 offset:57600
	ds_read_b128 v[180:183], v205 offset:59648
	ds_read_b128 v[184:187], v205 offset:61696
	s_waitcnt lgkmcnt(11)
	v_mfma_f32_16x16x32_bf16 v[32:35], v[100:103], v[88:91], v[32:35]
	global_load_lds_dwordx4 v216, s[6:7]
	v_mfma_f32_16x16x32_bf16 v[36:39], v[104:107], v[88:91], v[36:39]
	v_mfma_f32_16x16x32_bf16 v[40:43], v[108:111], v[88:91], v[40:43]
	v_mfma_f32_16x16x32_bf16 v[44:47], v[112:115], v[88:91], v[44:47]
	s_waitcnt lgkmcnt(10)
	v_mfma_f32_16x16x32_bf16 v[48:51], v[100:103], v[92:95], v[48:51]
	v_mfma_f32_16x16x32_bf16 v[52:55], v[104:107], v[92:95], v[52:55]
	v_mfma_f32_16x16x32_bf16 v[56:59], v[108:111], v[92:95], v[56:59]
	v_mfma_f32_16x16x32_bf16 v[60:63], v[112:115], v[92:95], v[60:63]
	s_waitcnt lgkmcnt(9)
	v_mfma_f32_16x16x32_bf16 v[64:67], v[100:103], v[96:99], v[64:67]
	v_mfma_f32_16x16x32_bf16 v[68:71], v[104:107], v[96:99], v[68:71]
	v_mfma_f32_16x16x32_bf16 v[72:75], v[108:111], v[96:99], v[72:75]
	v_mfma_f32_16x16x32_bf16 v[76:79], v[112:115], v[96:99], v[76:79]
	s_waitcnt lgkmcnt(7)
	v_mfma_f32_16x16x32_bf16 v[0:3], v[188:191], v[168:171], v[0:3]
	s_waitcnt lgkmcnt(6)
	v_mfma_f32_16x16x32_bf16 v[4:7], v[192:195], v[168:171], v[4:7]
	s_waitcnt lgkmcnt(5)
	v_mfma_f32_16x16x32_bf16 v[8:11], v[196:199], v[168:171], v[8:11]
	s_waitcnt lgkmcnt(4)
	v_mfma_f32_16x16x32_bf16 v[12:15], v[200:203], v[168:171], v[12:15]
	s_waitcnt lgkmcnt(3)
	v_mfma_f32_16x16x32_bf16 v[16:19], v[188:191], v[172:175], v[16:19]
	v_mfma_f32_16x16x32_bf16 v[20:23], v[192:195], v[172:175], v[20:23]
	v_mfma_f32_16x16x32_bf16 v[24:27], v[196:199], v[172:175], v[24:27]
	v_mfma_f32_16x16x32_bf16 v[28:31], v[200:203], v[172:175], v[28:31]
	s_waitcnt lgkmcnt(2)
	v_mfma_f32_16x16x32_bf16 v[32:35], v[188:191], v[176:179], v[32:35]
	v_mfma_f32_16x16x32_bf16 v[36:39], v[192:195], v[176:179], v[36:39]
	v_mfma_f32_16x16x32_bf16 v[40:43], v[196:199], v[176:179], v[40:43]
	v_mfma_f32_16x16x32_bf16 v[44:47], v[200:203], v[176:179], v[44:47]
	s_waitcnt lgkmcnt(1)
	v_mfma_f32_16x16x32_bf16 v[48:51], v[188:191], v[180:183], v[48:51]
	v_mfma_f32_16x16x32_bf16 v[52:55], v[192:195], v[180:183], v[52:55]
	v_mfma_f32_16x16x32_bf16 v[56:59], v[196:199], v[180:183], v[56:59]
	v_mfma_f32_16x16x32_bf16 v[60:63], v[200:203], v[180:183], v[60:63]
	s_add_u32 s2, s2, 0x80
	s_addc_u32 s3, s3, 0
	s_add_u32 s6, s6, 0x80
	s_addc_u32 s7, s7, 0
	s_waitcnt lgkmcnt(0)
	v_mfma_f32_16x16x32_bf16 v[64:67], v[188:191], v[184:187], v[64:67]
	v_mfma_f32_16x16x32_bf16 v[68:71], v[192:195], v[184:187], v[68:71]
	v_mfma_f32_16x16x32_bf16 v[72:75], v[196:199], v[184:187], v[72:75]
	v_mfma_f32_16x16x32_bf16 v[76:79], v[200:203], v[184:187], v[76:79]
	s_sub_u32 s12, s12, 1
	s_cmp_lg_u32 s12, 0
	s_cbranch_scc1 .Lggu0_pair
	s_and_b32 s4, s10, 7
	s_lshl_b32 s4, s4, 3
	s_bfe_u32 s14, s10, 0x30003
	s_or_b32 s14, s14, s4
	s_lshr_b32 s15, s10, 6
	s_mul_i32 s4, s14, 0xdc000
	s_lshl_b32 s32, s15, 7
	s_add_u32 s4, s4, s32
	s_add_u32 s8, s76, s4
	s_addc_u32 s9, s77, 0
	s_nop 7
	v_mul_f32_e32 v220, 0xbfb8aa3b, v0
	v_mul_f32_e32 v221, 0xbfb8aa3b, v1
	v_mul_f32_e32 v222, 0xbfb8aa3b, v2
	v_mul_f32_e32 v223, 0xbfb8aa3b, v3
	v_exp_f32_e32 v220, v220
	v_exp_f32_e32 v221, v221
	v_exp_f32_e32 v222, v222
	v_exp_f32_e32 v223, v223
	s_nop 0
	v_add_f32_e32 v220, 1.0, v220
	v_add_f32_e32 v221, 1.0, v221
	v_add_f32_e32 v222, 1.0, v222
	v_add_f32_e32 v223, 1.0, v223
	v_rcp_f32_e32 v220, v220
	v_rcp_f32_e32 v221, v221
	v_rcp_f32_e32 v222, v222
	v_rcp_f32_e32 v223, v223
	s_nop 0
	v_mul_f32_e32 v220, v0, v220
	v_mul_f32_e32 v221, v1, v221
	v_mul_f32_e32 v222, v2, v222
	v_mul_f32_e32 v223, v3, v223
	v_mul_f32_e32 v220, v4, v220
	v_mul_f32_e32 v221, v5, v221
	v_mul_f32_e32 v222, v6, v222
	v_mul_f32_e32 v223, v7, v223
	v_mul_f32_e32 v228, 0xbfb8aa3b, v8
	v_mul_f32_e32 v229, 0xbfb8aa3b, v9
	v_mul_f32_e32 v230, 0xbfb8aa3b, v10
	v_mul_f32_e32 v231, 0xbfb8aa3b, v11
	v_exp_f32_e32 v228, v228
	v_exp_f32_e32 v229, v229
	v_exp_f32_e32 v230, v230
	v_exp_f32_e32 v231, v231
	s_nop 0
	v_add_f32_e32 v228, 1.0, v228
	v_add_f32_e32 v229, 1.0, v229
	v_add_f32_e32 v230, 1.0, v230
	v_add_f32_e32 v231, 1.0, v231
	v_rcp_f32_e32 v228, v228
	v_rcp_f32_e32 v229, v229
	v_rcp_f32_e32 v230, v230
	v_rcp_f32_e32 v231, v231
	s_nop 0
	v_mul_f32_e32 v228, v8, v228
	v_mul_f32_e32 v229, v9, v229
	v_mul_f32_e32 v230, v10, v230
	v_mul_f32_e32 v231, v11, v231
	v_mul_f32_e32 v228, v12, v228
	v_mul_f32_e32 v229, v13, v229
	v_mul_f32_e32 v230, v14, v230
	v_mul_f32_e32 v231, v15, v231
	v_cvt_pk_bf16_f32 v80, v220, v221
	v_cvt_pk_bf16_f32 v81, v222, v223
	v_cvt_pk_bf16_f32 v82, v228, v229
	v_cvt_pk_bf16_f32 v83, v230, v231
	global_store_dwordx4 v217, v[80:83], s[8:9]
	s_add_u32 s8, s8, 0x16000
	s_addc_u32 s9, s9, 0
	v_mul_f32_e32 v220, 0xbfb8aa3b, v16
	v_mul_f32_e32 v221, 0xbfb8aa3b, v17
	v_mul_f32_e32 v222, 0xbfb8aa3b, v18
	v_mul_f32_e32 v223, 0xbfb8aa3b, v19
	v_exp_f32_e32 v220, v220
	v_exp_f32_e32 v221, v221
	v_exp_f32_e32 v222, v222
	v_exp_f32_e32 v223, v223
	s_nop 0
	v_add_f32_e32 v220, 1.0, v220
	v_add_f32_e32 v221, 1.0, v221
	v_add_f32_e32 v222, 1.0, v222
	v_add_f32_e32 v223, 1.0, v223
	v_rcp_f32_e32 v220, v220
	v_rcp_f32_e32 v221, v221
	v_rcp_f32_e32 v222, v222
	v_rcp_f32_e32 v223, v223
	s_nop 0
	v_mul_f32_e32 v220, v16, v220
	v_mul_f32_e32 v221, v17, v221
	v_mul_f32_e32 v222, v18, v222
	v_mul_f32_e32 v223, v19, v223
	v_mul_f32_e32 v220, v20, v220
	v_mul_f32_e32 v221, v21, v221
	v_mul_f32_e32 v222, v22, v222
	v_mul_f32_e32 v223, v23, v223
	v_mul_f32_e32 v228, 0xbfb8aa3b, v24
	v_mul_f32_e32 v229, 0xbfb8aa3b, v25
	v_mul_f32_e32 v230, 0xbfb8aa3b, v26
	v_mul_f32_e32 v231, 0xbfb8aa3b, v27
	v_exp_f32_e32 v228, v228
	v_exp_f32_e32 v229, v229
	v_exp_f32_e32 v230, v230
	v_exp_f32_e32 v231, v231
	s_nop 0
	v_add_f32_e32 v228, 1.0, v228
	v_add_f32_e32 v229, 1.0, v229
	v_add_f32_e32 v230, 1.0, v230
	v_add_f32_e32 v231, 1.0, v231
	v_rcp_f32_e32 v228, v228
	v_rcp_f32_e32 v229, v229
	v_rcp_f32_e32 v230, v230
	v_rcp_f32_e32 v231, v231
	s_nop 0
	v_mul_f32_e32 v228, v24, v228
	v_mul_f32_e32 v229, v25, v229
	v_mul_f32_e32 v230, v26, v230
	v_mul_f32_e32 v231, v27, v231
	v_mul_f32_e32 v228, v28, v228
	v_mul_f32_e32 v229, v29, v229
	v_mul_f32_e32 v230, v30, v230
	v_mul_f32_e32 v231, v31, v231
	v_cvt_pk_bf16_f32 v84, v220, v221
	v_cvt_pk_bf16_f32 v85, v222, v223
	v_cvt_pk_bf16_f32 v86, v228, v229
	v_cvt_pk_bf16_f32 v87, v230, v231
	global_store_dwordx4 v217, v[84:87], s[8:9]
	s_add_u32 s8, s8, 0x16000
	s_addc_u32 s9, s9, 0
	v_mul_f32_e32 v220, 0xbfb8aa3b, v32
	v_mul_f32_e32 v221, 0xbfb8aa3b, v33
	v_mul_f32_e32 v222, 0xbfb8aa3b, v34
	v_mul_f32_e32 v223, 0xbfb8aa3b, v35
	v_exp_f32_e32 v220, v220
	v_exp_f32_e32 v221, v221
	v_exp_f32_e32 v222, v222
	v_exp_f32_e32 v223, v223
	s_nop 0
	v_add_f32_e32 v220, 1.0, v220
	v_add_f32_e32 v221, 1.0, v221
	v_add_f32_e32 v222, 1.0, v222
	v_add_f32_e32 v223, 1.0, v223
	v_rcp_f32_e32 v220, v220
	v_rcp_f32_e32 v221, v221
	v_rcp_f32_e32 v222, v222
	v_rcp_f32_e32 v223, v223
	s_nop 0
	v_mul_f32_e32 v220, v32, v220
	v_mul_f32_e32 v221, v33, v221
	v_mul_f32_e32 v222, v34, v222
	v_mul_f32_e32 v223, v35, v223
	v_mul_f32_e32 v220, v36, v220
	v_mul_f32_e32 v221, v37, v221
	v_mul_f32_e32 v222, v38, v222
	v_mul_f32_e32 v223, v39, v223
	v_mul_f32_e32 v228, 0xbfb8aa3b, v40
	v_mul_f32_e32 v229, 0xbfb8aa3b, v41
	v_mul_f32_e32 v230, 0xbfb8aa3b, v42
	v_mul_f32_e32 v231, 0xbfb8aa3b, v43
	v_exp_f32_e32 v228, v228
	v_exp_f32_e32 v229, v229
	v_exp_f32_e32 v230, v230
	v_exp_f32_e32 v231, v231
	s_nop 0
	v_add_f32_e32 v228, 1.0, v228
	v_add_f32_e32 v229, 1.0, v229
	v_add_f32_e32 v230, 1.0, v230
	v_add_f32_e32 v231, 1.0, v231
	v_rcp_f32_e32 v228, v228
	v_rcp_f32_e32 v229, v229
	v_rcp_f32_e32 v230, v230
	v_rcp_f32_e32 v231, v231
	s_nop 0
	v_mul_f32_e32 v228, v40, v228
	v_mul_f32_e32 v229, v41, v229
	v_mul_f32_e32 v230, v42, v230
	v_mul_f32_e32 v231, v43, v231
	v_mul_f32_e32 v228, v44, v228
	v_mul_f32_e32 v229, v45, v229
	v_mul_f32_e32 v230, v46, v230
	v_mul_f32_e32 v231, v47, v231
	v_cvt_pk_bf16_f32 v88, v220, v221
	v_cvt_pk_bf16_f32 v89, v222, v223
	v_cvt_pk_bf16_f32 v90, v228, v229
	v_cvt_pk_bf16_f32 v91, v230, v231
	global_store_dwordx4 v217, v[88:91], s[8:9]
	s_add_u32 s8, s8, 0x16000
	s_addc_u32 s9, s9, 0
	v_mul_f32_e32 v220, 0xbfb8aa3b, v48
	v_mul_f32_e32 v221, 0xbfb8aa3b, v49
	v_mul_f32_e32 v222, 0xbfb8aa3b, v50
	v_mul_f32_e32 v223, 0xbfb8aa3b, v51
	v_exp_f32_e32 v220, v220
	v_exp_f32_e32 v221, v221
	v_exp_f32_e32 v222, v222
	v_exp_f32_e32 v223, v223
	s_nop 0
	v_add_f32_e32 v220, 1.0, v220
	v_add_f32_e32 v221, 1.0, v221
	v_add_f32_e32 v222, 1.0, v222
	v_add_f32_e32 v223, 1.0, v223
	v_rcp_f32_e32 v220, v220
	v_rcp_f32_e32 v221, v221
	v_rcp_f32_e32 v222, v222
	v_rcp_f32_e32 v223, v223
	s_nop 0
	v_mul_f32_e32 v220, v48, v220
	v_mul_f32_e32 v221, v49, v221
	v_mul_f32_e32 v222, v50, v222
	v_mul_f32_e32 v223, v51, v223
	v_mul_f32_e32 v220, v52, v220
	v_mul_f32_e32 v221, v53, v221
	v_mul_f32_e32 v222, v54, v222
	v_mul_f32_e32 v223, v55, v223
	v_mul_f32_e32 v228, 0xbfb8aa3b, v56
	v_mul_f32_e32 v229, 0xbfb8aa3b, v57
	v_mul_f32_e32 v230, 0xbfb8aa3b, v58
	v_mul_f32_e32 v231, 0xbfb8aa3b, v59
	v_exp_f32_e32 v228, v228
	v_exp_f32_e32 v229, v229
	v_exp_f32_e32 v230, v230
	v_exp_f32_e32 v231, v231
	s_nop 0
	v_add_f32_e32 v228, 1.0, v228
	v_add_f32_e32 v229, 1.0, v229
	v_add_f32_e32 v230, 1.0, v230
	v_add_f32_e32 v231, 1.0, v231
	v_rcp_f32_e32 v228, v228
	v_rcp_f32_e32 v229, v229
	v_rcp_f32_e32 v230, v230
	v_rcp_f32_e32 v231, v231
	s_nop 0
	v_mul_f32_e32 v228, v56, v228
	v_mul_f32_e32 v229, v57, v229
	v_mul_f32_e32 v230, v58, v230
	v_mul_f32_e32 v231, v59, v231
	v_mul_f32_e32 v228, v60, v228
	v_mul_f32_e32 v229, v61, v229
	v_mul_f32_e32 v230, v62, v230
	v_mul_f32_e32 v231, v63, v231
	v_cvt_pk_bf16_f32 v92, v220, v221
	v_cvt_pk_bf16_f32 v93, v222, v223
	v_cvt_pk_bf16_f32 v94, v228, v229
	v_cvt_pk_bf16_f32 v95, v230, v231
	global_store_dwordx4 v217, v[92:95], s[8:9]
	s_add_u32 s8, s8, 0x16000
	s_addc_u32 s9, s9, 0
	v_mul_f32_e32 v220, 0xbfb8aa3b, v64
	v_mul_f32_e32 v221, 0xbfb8aa3b, v65
	v_mul_f32_e32 v222, 0xbfb8aa3b, v66
	v_mul_f32_e32 v223, 0xbfb8aa3b, v67
	v_exp_f32_e32 v220, v220
	v_exp_f32_e32 v221, v221
	v_exp_f32_e32 v222, v222
	v_exp_f32_e32 v223, v223
	s_nop 0
	v_add_f32_e32 v220, 1.0, v220
	v_add_f32_e32 v221, 1.0, v221
	v_add_f32_e32 v222, 1.0, v222
	v_add_f32_e32 v223, 1.0, v223
	v_rcp_f32_e32 v220, v220
	v_rcp_f32_e32 v221, v221
	v_rcp_f32_e32 v222, v222
	v_rcp_f32_e32 v223, v223
	s_nop 0
	v_mul_f32_e32 v220, v64, v220
	v_mul_f32_e32 v221, v65, v221
	v_mul_f32_e32 v222, v66, v222
	v_mul_f32_e32 v223, v67, v223
	v_mul_f32_e32 v220, v68, v220
	v_mul_f32_e32 v221, v69, v221
	v_mul_f32_e32 v222, v70, v222
	v_mul_f32_e32 v223, v71, v223
	v_mul_f32_e32 v228, 0xbfb8aa3b, v72
	v_mul_f32_e32 v229, 0xbfb8aa3b, v73
	v_mul_f32_e32 v230, 0xbfb8aa3b, v74
	v_mul_f32_e32 v231, 0xbfb8aa3b, v75
	v_exp_f32_e32 v228, v228
	v_exp_f32_e32 v229, v229
	v_exp_f32_e32 v230, v230
	v_exp_f32_e32 v231, v231
	s_nop 0
	v_add_f32_e32 v228, 1.0, v228
	v_add_f32_e32 v229, 1.0, v229
	v_add_f32_e32 v230, 1.0, v230
	v_add_f32_e32 v231, 1.0, v231
	v_rcp_f32_e32 v228, v228
	v_rcp_f32_e32 v229, v229
	v_rcp_f32_e32 v230, v230
	v_rcp_f32_e32 v231, v231
	s_nop 0
	v_mul_f32_e32 v228, v72, v228
	v_mul_f32_e32 v229, v73, v229
	v_mul_f32_e32 v230, v74, v230
	v_mul_f32_e32 v231, v75, v231
	v_mul_f32_e32 v228, v76, v228
	v_mul_f32_e32 v229, v77, v229
	v_mul_f32_e32 v230, v78, v230
	v_mul_f32_e32 v231, v79, v231
	v_cvt_pk_bf16_f32 v96, v220, v221
	v_cvt_pk_bf16_f32 v97, v222, v223
	v_cvt_pk_bf16_f32 v98, v228, v229
	v_cvt_pk_bf16_f32 v99, v230, v231
	global_store_dwordx4 v217, v[96:99], s[8:9]
	s_add_u32 s10, s10, s11
	s_cmp_lt_u32 s10, 0xb00
	s_cbranch_scc1 .Lggu0_tile

.Lgdn0_pair:
	s_waitcnt vmcnt(0)
	s_barrier
	ds_read_b128 v[80:83], v204 offset:0
	ds_read_b128 v[100:103], v206 offset:20480
	ds_read_b128 v[104:107], v206 offset:22528
	ds_read_b128 v[108:111], v206 offset:24576
	ds_read_b128 v[112:115], v206 offset:26624
	ds_read_b128 v[84:87], v204 offset:2048
	ds_read_b128 v[88:91], v204 offset:4096
	ds_read_b128 v[92:95], v204 offset:6144
	ds_read_b128 v[96:99], v204 offset:8192
	s_add_u32 m0, s13, 0xd100
	s_waitcnt lgkmcnt(7)
	v_mfma_f32_16x16x32_bf16 v[0:3], v[100:103], v[80:83], v[0:3]
	global_load_lds_dwordx4 v208, s[2:3]
	s_add_u32 m0, s13, 0xe100
	s_waitcnt lgkmcnt(6)
	v_mfma_f32_16x16x32_bf16 v[4:7], v[104:107], v[80:83], v[4:7]
	global_load_lds_dwordx4 v209, s[2:3]
	s_add_u32 m0, s13, 0xf100
	s_waitcnt lgkmcnt(5)
	v_mfma_f32_16x16x32_bf16 v[8:11], v[108:111], v[80:83], v[8:11]
	global_load_lds_dwordx4 v210, s[2:3]
	s_add_u32 m0, s13, 0x10100
	s_waitcnt lgkmcnt(4)
	v_mfma_f32_16x16x32_bf16 v[12:15], v[112:115], v[80:83], v[12:15]
	global_load_lds_dwordx4 v211, s[2:3]
	s_add_u32 m0, s13, 0x11100
	ds_read_b128 v[168:171], v205 offset:0
	ds_read_b128 v[188:191], v207 offset:20480
	ds_read_b128 v[192:195], v207 offset:22528
	ds_read_b128 v[196:199], v207 offset:24576
	ds_read_b128 v[200:203], v207 offset:26624
	s_waitcnt lgkmcnt(8)
	v_mfma_f32_16x16x32_bf16 v[16:19], v[100:103], v[84:87], v[16:19]
	global_load_lds_dwordx4 v212, s[2:3]
	s_add_u32 m0, s13, 0x9000
	v_mfma_f32_16x16x32_bf16 v[20:23], v[104:107], v[84:87], v[20:23]
	global_load_lds_dwordx4 v213, s[6:7]
	s_add_u32 m0, s13, 0xa000
	v_mfma_f32_16x16x32_bf16 v[24:27], v[108:111], v[84:87], v[24:27]
	global_load_lds_dwordx4 v214, s[6:7]
	s_add_u32 m0, s13, 0xb000
	v_mfma_f32_16x16x32_bf16 v[28:31], v[112:115], v[84:87], v[28:31]
	global_load_lds_dwordx4 v215, s[6:7]
	s_add_u32 m0, s13, 0xc000
	ds_read_b128 v[172:175], v205 offset:2048
	ds_read_b128 v[176:179], v205 offset:4096
	ds_read_b128 v[180:183], v205 offset:6144
	ds_read_b128 v[184:187], v205 offset:8192
	s_waitcnt lgkmcnt(11)
	v_mfma_f32_16x16x32_bf16 v[32:35], v[100:103], v[88:91], v[32:35]
	global_load_lds_dwordx4 v216, s[6:7]
	v_mfma_f32_16x16x32_bf16 v[36:39], v[104:107], v[88:91], v[36:39]
	v_mfma_f32_16x16x32_bf16 v[40:43], v[108:111], v[88:91], v[40:43]
	v_mfma_f32_16x16x32_bf16 v[44:47], v[112:115], v[88:91], v[44:47]
	s_waitcnt lgkmcnt(10)
	v_mfma_f32_16x16x32_bf16 v[48:51], v[100:103], v[92:95], v[48:51]
	v_mfma_f32_16x16x32_bf16 v[52:55], v[104:107], v[92:95], v[52:55]
	v_mfma_f32_16x16x32_bf16 v[56:59], v[108:111], v[92:95], v[56:59]
	v_mfma_f32_16x16x32_bf16 v[60:63], v[112:115], v[92:95], v[60:63]
	s_waitcnt lgkmcnt(9)
	v_mfma_f32_16x16x32_bf16 v[64:67], v[100:103], v[96:99], v[64:67]
	v_mfma_f32_16x16x32_bf16 v[68:71], v[104:107], v[96:99], v[68:71]
	v_mfma_f32_16x16x32_bf16 v[72:75], v[108:111], v[96:99], v[72:75]
	v_mfma_f32_16x16x32_bf16 v[76:79], v[112:115], v[96:99], v[76:79]
	s_waitcnt lgkmcnt(7)
	v_mfma_f32_16x16x32_bf16 v[0:3], v[188:191], v[168:171], v[0:3]
	s_waitcnt lgkmcnt(6)
	v_mfma_f32_16x16x32_bf16 v[4:7], v[192:195], v[168:171], v[4:7]
	s_waitcnt lgkmcnt(5)
	v_mfma_f32_16x16x32_bf16 v[8:11], v[196:199], v[168:171], v[8:11]
	s_waitcnt lgkmcnt(4)
	v_mfma_f32_16x16x32_bf16 v[12:15], v[200:203], v[168:171], v[12:15]
	s_waitcnt lgkmcnt(3)
	v_mfma_f32_16x16x32_bf16 v[16:19], v[188:191], v[172:175], v[16:19]
	v_mfma_f32_16x16x32_bf16 v[20:23], v[192:195], v[172:175], v[20:23]
	v_mfma_f32_16x16x32_bf16 v[24:27], v[196:199], v[172:175], v[24:27]
	v_mfma_f32_16x16x32_bf16 v[28:31], v[200:203], v[172:175], v[28:31]
	s_waitcnt lgkmcnt(2)
	v_mfma_f32_16x16x32_bf16 v[32:35], v[188:191], v[176:179], v[32:35]
	v_mfma_f32_16x16x32_bf16 v[36:39], v[192:195], v[176:179], v[36:39]
	v_mfma_f32_16x16x32_bf16 v[40:43], v[196:199], v[176:179], v[40:43]
	v_mfma_f32_16x16x32_bf16 v[44:47], v[200:203], v[176:179], v[44:47]
	s_waitcnt lgkmcnt(1)
	v_mfma_f32_16x16x32_bf16 v[48:51], v[188:191], v[180:183], v[48:51]
	v_mfma_f32_16x16x32_bf16 v[52:55], v[192:195], v[180:183], v[52:55]
	v_mfma_f32_16x16x32_bf16 v[56:59], v[196:199], v[180:183], v[56:59]
	v_mfma_f32_16x16x32_bf16 v[60:63], v[200:203], v[180:183], v[60:63]
	s_add_u32 s2, s2, 0x80
	s_addc_u32 s3, s3, 0
	s_add_u32 s6, s6, 0x80
	s_addc_u32 s7, s7, 0
	s_waitcnt lgkmcnt(0)
	v_mfma_f32_16x16x32_bf16 v[64:67], v[188:191], v[184:187], v[64:67]
	v_mfma_f32_16x16x32_bf16 v[68:71], v[192:195], v[184:187], v[68:71]
	v_mfma_f32_16x16x32_bf16 v[72:75], v[196:199], v[184:187], v[72:75]
	v_mfma_f32_16x16x32_bf16 v[76:79], v[200:203], v[184:187], v[76:79]
	s_cmp_eq_u32 s12, 1
	s_cselect_b32 s2, s20, s2
	s_cselect_b32 s3, s21, s3
	s_cselect_b32 s6, s22, s6
	s_cselect_b32 s7, s23, s7
	s_waitcnt vmcnt(0)
	s_barrier
	ds_read_b128 v[80:83], v204 offset:53504
	ds_read_b128 v[100:103], v206 offset:36864
	ds_read_b128 v[104:107], v206 offset:38912
	ds_read_b128 v[108:111], v206 offset:40960
	ds_read_b128 v[112:115], v206 offset:43008
	ds_read_b128 v[84:87], v204 offset:55552
	ds_read_b128 v[88:91], v204 offset:57600
	ds_read_b128 v[92:95], v204 offset:59648
	ds_read_b128 v[96:99], v204 offset:61696
	s_add_u32 m0, s13, 0x0
	s_waitcnt lgkmcnt(7)
	v_mfma_f32_16x16x32_bf16 v[0:3], v[100:103], v[80:83], v[0:3]
	global_load_lds_dwordx4 v208, s[2:3]
	s_add_u32 m0, s13, 0x1000
	s_waitcnt lgkmcnt(6)
	v_mfma_f32_16x16x32_bf16 v[4:7], v[104:107], v[80:83], v[4:7]
	global_load_lds_dwordx4 v209, s[2:3]
	s_add_u32 m0, s13, 0x2000
	s_waitcnt lgkmcnt(5)
	v_mfma_f32_16x16x32_bf16 v[8:11], v[108:111], v[80:83], v[8:11]
	global_load_lds_dwordx4 v210, s[2:3]
	s_add_u32 m0, s13, 0x3000
	s_waitcnt lgkmcnt(4)
	v_mfma_f32_16x16x32_bf16 v[12:15], v[112:115], v[80:83], v[12:15]
	global_load_lds_dwordx4 v211, s[2:3]
	s_add_u32 m0, s13, 0x4000
	ds_read_b128 v[168:171], v205 offset:53504
	ds_read_b128 v[188:191], v207 offset:36864
	ds_read_b128 v[192:195], v207 offset:38912
	ds_read_b128 v[196:199], v207 offset:40960
	ds_read_b128 v[200:203], v207 offset:43008
	s_waitcnt lgkmcnt(8)
	v_mfma_f32_16x16x32_bf16 v[16:19], v[100:103], v[84:87], v[16:19]
	global_load_lds_dwordx4 v212, s[2:3]
	s_add_u32 m0, s13, 0x5000
	v_mfma_f32_16x16x32_bf16 v[20:23], v[104:107], v[84:87], v[20:23]
	global_load_lds_dwordx4 v213, s[6:7]
	s_add_u32 m0, s13, 0x6000
	v_mfma_f32_16x16x32_bf16 v[24:27], v[108:111], v[84:87], v[24:27]
	global_load_lds_dwordx4 v214, s[6:7]
	s_add_u32 m0, s13, 0x7000
	v_mfma_f32_16x16x32_bf16 v[28:31], v[112:115], v[84:87], v[28:31]
	global_load_lds_dwordx4 v215, s[6:7]
	s_add_u32 m0, s13, 0x8000
	ds_read_b128 v[172:175], v205 offset:55552
	ds_read_b128 v[176:179], v205 offset:57600
	ds_read_b128 v[180:183], v205 offset:59648
	ds_read_b128 v[184:187], v205 offset:61696
	s_waitcnt lgkmcnt(11)
	v_mfma_f32_16x16x32_bf16 v[32:35], v[100:103], v[88:91], v[32:35]
	global_load_lds_dwordx4 v216, s[6:7]
	v_mfma_f32_16x16x32_bf16 v[36:39], v[104:107], v[88:91], v[36:39]
	v_mfma_f32_16x16x32_bf16 v[40:43], v[108:111], v[88:91], v[40:43]
	v_mfma_f32_16x16x32_bf16 v[44:47], v[112:115], v[88:91], v[44:47]
	s_waitcnt lgkmcnt(10)
	v_mfma_f32_16x16x32_bf16 v[48:51], v[100:103], v[92:95], v[48:51]
	v_mfma_f32_16x16x32_bf16 v[52:55], v[104:107], v[92:95], v[52:55]
	v_mfma_f32_16x16x32_bf16 v[56:59], v[108:111], v[92:95], v[56:59]
	v_mfma_f32_16x16x32_bf16 v[60:63], v[112:115], v[92:95], v[60:63]
	s_waitcnt lgkmcnt(9)
	v_mfma_f32_16x16x32_bf16 v[64:67], v[100:103], v[96:99], v[64:67]
	v_mfma_f32_16x16x32_bf16 v[68:71], v[104:107], v[96:99], v[68:71]
	v_mfma_f32_16x16x32_bf16 v[72:75], v[108:111], v[96:99], v[72:75]
	v_mfma_f32_16x16x32_bf16 v[76:79], v[112:115], v[96:99], v[76:79]
	s_waitcnt lgkmcnt(7)
	v_mfma_f32_16x16x32_bf16 v[0:3], v[188:191], v[168:171], v[0:3]
	s_waitcnt lgkmcnt(6)
	v_mfma_f32_16x16x32_bf16 v[4:7], v[192:195], v[168:171], v[4:7]
	s_waitcnt lgkmcnt(5)
	v_mfma_f32_16x16x32_bf16 v[8:11], v[196:199], v[168:171], v[8:11]
	s_waitcnt lgkmcnt(4)
	v_mfma_f32_16x16x32_bf16 v[12:15], v[200:203], v[168:171], v[12:15]
	s_waitcnt lgkmcnt(3)
	v_mfma_f32_16x16x32_bf16 v[16:19], v[188:191], v[172:175], v[16:19]
	v_mfma_f32_16x16x32_bf16 v[20:23], v[192:195], v[172:175], v[20:23]
	v_mfma_f32_16x16x32_bf16 v[24:27], v[196:199], v[172:175], v[24:27]
	v_mfma_f32_16x16x32_bf16 v[28:31], v[200:203], v[172:175], v[28:31]
	s_waitcnt lgkmcnt(2)
	v_mfma_f32_16x16x32_bf16 v[32:35], v[188:191], v[176:179], v[32:35]
	v_mfma_f32_16x16x32_bf16 v[36:39], v[192:195], v[176:179], v[36:39]
	v_mfma_f32_16x16x32_bf16 v[40:43], v[196:199], v[176:179], v[40:43]
	v_mfma_f32_16x16x32_bf16 v[44:47], v[200:203], v[176:179], v[44:47]
	s_waitcnt lgkmcnt(1)
	v_mfma_f32_16x16x32_bf16 v[48:51], v[188:191], v[180:183], v[48:51]
	v_mfma_f32_16x16x32_bf16 v[52:55], v[192:195], v[180:183], v[52:55]
	v_mfma_f32_16x16x32_bf16 v[56:59], v[196:199], v[180:183], v[56:59]
	v_mfma_f32_16x16x32_bf16 v[60:63], v[200:203], v[180:183], v[60:63]
	s_add_u32 s2, s2, 0x80
	s_addc_u32 s3, s3, 0
	s_add_u32 s6, s6, 0x80
	s_addc_u32 s7, s7, 0
	s_waitcnt lgkmcnt(0)
	v_mfma_f32_16x16x32_bf16 v[64:67], v[188:191], v[184:187], v[64:67]
	v_mfma_f32_16x16x32_bf16 v[68:71], v[192:195], v[184:187], v[68:71]
	v_mfma_f32_16x16x32_bf16 v[72:75], v[196:199], v[184:187], v[72:75]
	v_mfma_f32_16x16x32_bf16 v[76:79], v[200:203], v[184:187], v[76:79]
	s_sub_u32 s12, s12, 1
	s_cmp_lg_u32 s12, 0
	s_cbranch_scc1 .Lgdn0_pair
	s_and_b32 s4, s10, 7
	s_lshl_b32 s4, s4, 3
	s_bfe_u32 s14, s10, 0x30003
	s_or_b32 s14, s14, s4
	s_lshr_b32 s15, s10, 6
	s_mul_i32 s4, s14, 0x50000
	s_lshl_b32 s32, s15, 8
	s_add_u32 s4, s4, s32
	s_add_u32 s8, s78, s4
	s_addc_u32 s9, s79, 0
	s_nop 7
	v_cvt_pk_bf16_f32 v80, v0, v1
	v_cvt_pk_bf16_f32 v81, v2, v3
	v_cvt_pk_bf16_f32 v82, v4, v5
	v_cvt_pk_bf16_f32 v83, v6, v7
	global_store_dwordx4 v217, v[80:83], s[8:9]
	v_cvt_pk_bf16_f32 v84, v8, v9
	v_cvt_pk_bf16_f32 v85, v10, v11
	v_cvt_pk_bf16_f32 v86, v12, v13
	v_cvt_pk_bf16_f32 v87, v14, v15
	global_store_dwordx4 v217, v[84:87], s[8:9] offset:64
	s_add_u32 s8, s8, 0x8000
	s_addc_u32 s9, s9, 0
	v_cvt_pk_bf16_f32 v88, v16, v17
	v_cvt_pk_bf16_f32 v89, v18, v19
	v_cvt_pk_bf16_f32 v90, v20, v21
	v_cvt_pk_bf16_f32 v91, v22, v23
	global_store_dwordx4 v217, v[88:91], s[8:9]
	v_cvt_pk_bf16_f32 v92, v24, v25
	v_cvt_pk_bf16_f32 v93, v26, v27
	v_cvt_pk_bf16_f32 v94, v28, v29
	v_cvt_pk_bf16_f32 v95, v30, v31
	global_store_dwordx4 v217, v[92:95], s[8:9] offset:64
	s_add_u32 s8, s8, 0x8000
	s_addc_u32 s9, s9, 0
	v_cvt_pk_bf16_f32 v96, v32, v33
	v_cvt_pk_bf16_f32 v97, v34, v35
	v_cvt_pk_bf16_f32 v98, v36, v37
	v_cvt_pk_bf16_f32 v99, v38, v39
	global_store_dwordx4 v217, v[96:99], s[8:9]
	v_cvt_pk_bf16_f32 v100, v40, v41
	v_cvt_pk_bf16_f32 v101, v42, v43
	v_cvt_pk_bf16_f32 v102, v44, v45
	v_cvt_pk_bf16_f32 v103, v46, v47
	global_store_dwordx4 v217, v[100:103], s[8:9] offset:64
	s_add_u32 s8, s8, 0x8000
	s_addc_u32 s9, s9, 0
	v_cvt_pk_bf16_f32 v104, v48, v49
	v_cvt_pk_bf16_f32 v105, v50, v51
	v_cvt_pk_bf16_f32 v106, v52, v53
	v_cvt_pk_bf16_f32 v107, v54, v55
	global_store_dwordx4 v217, v[104:107], s[8:9]
	v_cvt_pk_bf16_f32 v108, v56, v57
	v_cvt_pk_bf16_f32 v109, v58, v59
	v_cvt_pk_bf16_f32 v110, v60, v61
	v_cvt_pk_bf16_f32 v111, v62, v63
	global_store_dwordx4 v217, v[108:111], s[8:9] offset:64
	s_add_u32 s8, s8, 0x8000
	s_addc_u32 s9, s9, 0
	v_cvt_pk_bf16_f32 v112, v64, v65
	v_cvt_pk_bf16_f32 v113, v66, v67
	v_cvt_pk_bf16_f32 v114, v68, v69
	v_cvt_pk_bf16_f32 v115, v70, v71
	global_store_dwordx4 v217, v[112:115], s[8:9]
	v_cvt_pk_bf16_f32 v80, v72, v73
	v_cvt_pk_bf16_f32 v81, v74, v75
	v_cvt_pk_bf16_f32 v82, v76, v77
	v_cvt_pk_bf16_f32 v83, v78, v79
	global_store_dwordx4 v217, v[80:83], s[8:9] offset:64
	s_add_u32 s10, s10, s11
	s_cmp_lt_u32 s10, 0x200
	s_cbranch_scc1 .Lgdn0_tile

.Lgzin_pair:
	s_waitcnt vmcnt(0)
	s_barrier
	ds_read_b128 v[80:83], v204 offset:0
	ds_read_b128 v[100:103], v206 offset:20480
	ds_read_b128 v[104:107], v206 offset:22528
	ds_read_b128 v[108:111], v206 offset:24576
	ds_read_b128 v[112:115], v206 offset:26624
	ds_read_b128 v[84:87], v204 offset:2048
	ds_read_b128 v[88:91], v204 offset:4096
	ds_read_b128 v[92:95], v204 offset:6144
	ds_read_b128 v[96:99], v204 offset:8192
	s_add_u32 m0, s13, 0xd100
	s_waitcnt lgkmcnt(7)
	v_mfma_f32_16x16x32_bf16 v[0:3], v[100:103], v[80:83], v[0:3]
	global_load_lds_dwordx4 v208, s[2:3]
	s_add_u32 m0, s13, 0xe100
	s_waitcnt lgkmcnt(6)
	v_mfma_f32_16x16x32_bf16 v[4:7], v[104:107], v[80:83], v[4:7]
	global_load_lds_dwordx4 v209, s[2:3]
	s_add_u32 m0, s13, 0xf100
	s_waitcnt lgkmcnt(5)
	v_mfma_f32_16x16x32_bf16 v[8:11], v[108:111], v[80:83], v[8:11]
	global_load_lds_dwordx4 v210, s[2:3]
	s_add_u32 m0, s13, 0x10100
	s_waitcnt lgkmcnt(4)
	v_mfma_f32_16x16x32_bf16 v[12:15], v[112:115], v[80:83], v[12:15]
	global_load_lds_dwordx4 v211, s[2:3]
	s_add_u32 m0, s13, 0x11100
	ds_read_b128 v[168:171], v205 offset:0
	ds_read_b128 v[188:191], v207 offset:20480
	ds_read_b128 v[192:195], v207 offset:22528
	ds_read_b128 v[196:199], v207 offset:24576
	ds_read_b128 v[200:203], v207 offset:26624
	s_waitcnt lgkmcnt(8)
	v_mfma_f32_16x16x32_bf16 v[16:19], v[100:103], v[84:87], v[16:19]
	global_load_lds_dwordx4 v212, s[2:3]
	s_add_u32 m0, s13, 0x9000
	v_mfma_f32_16x16x32_bf16 v[20:23], v[104:107], v[84:87], v[20:23]
	global_load_lds_dwordx4 v213, s[6:7]
	s_add_u32 m0, s13, 0xa000
	v_mfma_f32_16x16x32_bf16 v[24:27], v[108:111], v[84:87], v[24:27]
	global_load_lds_dwordx4 v214, s[6:7]
	s_add_u32 m0, s13, 0xb000
	v_mfma_f32_16x16x32_bf16 v[28:31], v[112:115], v[84:87], v[28:31]
	global_load_lds_dwordx4 v215, s[6:7]
	s_add_u32 m0, s13, 0xc000
	ds_read_b128 v[172:175], v205 offset:2048
	ds_read_b128 v[176:179], v205 offset:4096
	ds_read_b128 v[180:183], v205 offset:6144
	ds_read_b128 v[184:187], v205 offset:8192
	s_waitcnt lgkmcnt(11)
	v_mfma_f32_16x16x32_bf16 v[32:35], v[100:103], v[88:91], v[32:35]
	global_load_lds_dwordx4 v216, s[6:7]
	v_mfma_f32_16x16x32_bf16 v[36:39], v[104:107], v[88:91], v[36:39]
	v_mfma_f32_16x16x32_bf16 v[40:43], v[108:111], v[88:91], v[40:43]
	v_mfma_f32_16x16x32_bf16 v[44:47], v[112:115], v[88:91], v[44:47]
	s_waitcnt lgkmcnt(10)
	v_mfma_f32_16x16x32_bf16 v[48:51], v[100:103], v[92:95], v[48:51]
	v_mfma_f32_16x16x32_bf16 v[52:55], v[104:107], v[92:95], v[52:55]
	v_mfma_f32_16x16x32_bf16 v[56:59], v[108:111], v[92:95], v[56:59]
	v_mfma_f32_16x16x32_bf16 v[60:63], v[112:115], v[92:95], v[60:63]
	s_waitcnt lgkmcnt(9)
	v_mfma_f32_16x16x32_bf16 v[64:67], v[100:103], v[96:99], v[64:67]
	v_mfma_f32_16x16x32_bf16 v[68:71], v[104:107], v[96:99], v[68:71]
	v_mfma_f32_16x16x32_bf16 v[72:75], v[108:111], v[96:99], v[72:75]
	v_mfma_f32_16x16x32_bf16 v[76:79], v[112:115], v[96:99], v[76:79]
	s_waitcnt lgkmcnt(7)
	v_mfma_f32_16x16x32_bf16 v[0:3], v[188:191], v[168:171], v[0:3]
	s_waitcnt lgkmcnt(6)
	v_mfma_f32_16x16x32_bf16 v[4:7], v[192:195], v[168:171], v[4:7]
	s_waitcnt lgkmcnt(5)
	v_mfma_f32_16x16x32_bf16 v[8:11], v[196:199], v[168:171], v[8:11]
	s_waitcnt lgkmcnt(4)
	v_mfma_f32_16x16x32_bf16 v[12:15], v[200:203], v[168:171], v[12:15]
	s_waitcnt lgkmcnt(3)
	v_mfma_f32_16x16x32_bf16 v[16:19], v[188:191], v[172:175], v[16:19]
	v_mfma_f32_16x16x32_bf16 v[20:23], v[192:195], v[172:175], v[20:23]
	v_mfma_f32_16x16x32_bf16 v[24:27], v[196:199], v[172:175], v[24:27]
	v_mfma_f32_16x16x32_bf16 v[28:31], v[200:203], v[172:175], v[28:31]
	s_waitcnt lgkmcnt(2)
	v_mfma_f32_16x16x32_bf16 v[32:35], v[188:191], v[176:179], v[32:35]
	v_mfma_f32_16x16x32_bf16 v[36:39], v[192:195], v[176:179], v[36:39]
	v_mfma_f32_16x16x32_bf16 v[40:43], v[196:199], v[176:179], v[40:43]
	v_mfma_f32_16x16x32_bf16 v[44:47], v[200:203], v[176:179], v[44:47]
	s_waitcnt lgkmcnt(1)
	v_mfma_f32_16x16x32_bf16 v[48:51], v[188:191], v[180:183], v[48:51]
	v_mfma_f32_16x16x32_bf16 v[52:55], v[192:195], v[180:183], v[52:55]
	v_mfma_f32_16x16x32_bf16 v[56:59], v[196:199], v[180:183], v[56:59]
	v_mfma_f32_16x16x32_bf16 v[60:63], v[200:203], v[180:183], v[60:63]
	s_add_u32 s2, s2, 0x80
	s_addc_u32 s3, s3, 0
	s_add_u32 s6, s6, 0x80
	s_addc_u32 s7, s7, 0
	s_waitcnt lgkmcnt(0)
	v_mfma_f32_16x16x32_bf16 v[64:67], v[188:191], v[184:187], v[64:67]
	v_mfma_f32_16x16x32_bf16 v[68:71], v[192:195], v[184:187], v[68:71]
	v_mfma_f32_16x16x32_bf16 v[72:75], v[196:199], v[184:187], v[72:75]
	v_mfma_f32_16x16x32_bf16 v[76:79], v[200:203], v[184:187], v[76:79]
	s_cmp_eq_u32 s12, 1
	s_cselect_b32 s2, s20, s2
	s_cselect_b32 s3, s21, s3
	s_cselect_b32 s6, s22, s6
	s_cselect_b32 s7, s23, s7
	s_waitcnt vmcnt(0)
	s_barrier
	ds_read_b128 v[80:83], v204 offset:53504
	ds_read_b128 v[100:103], v206 offset:36864
	ds_read_b128 v[104:107], v206 offset:38912
	ds_read_b128 v[108:111], v206 offset:40960
	ds_read_b128 v[112:115], v206 offset:43008
	ds_read_b128 v[84:87], v204 offset:55552
	ds_read_b128 v[88:91], v204 offset:57600
	ds_read_b128 v[92:95], v204 offset:59648
	ds_read_b128 v[96:99], v204 offset:61696
	s_add_u32 m0, s13, 0x0
	s_waitcnt lgkmcnt(7)
	v_mfma_f32_16x16x32_bf16 v[0:3], v[100:103], v[80:83], v[0:3]
	global_load_lds_dwordx4 v208, s[2:3]
	s_add_u32 m0, s13, 0x1000
	s_waitcnt lgkmcnt(6)
	v_mfma_f32_16x16x32_bf16 v[4:7], v[104:107], v[80:83], v[4:7]
	global_load_lds_dwordx4 v209, s[2:3]
	s_add_u32 m0, s13, 0x2000
	s_waitcnt lgkmcnt(5)
	v_mfma_f32_16x16x32_bf16 v[8:11], v[108:111], v[80:83], v[8:11]
	global_load_lds_dwordx4 v210, s[2:3]
	s_add_u32 m0, s13, 0x3000
	s_waitcnt lgkmcnt(4)
	v_mfma_f32_16x16x32_bf16 v[12:15], v[112:115], v[80:83], v[12:15]
	global_load_lds_dwordx4 v211, s[2:3]
	s_add_u32 m0, s13, 0x4000
	ds_read_b128 v[168:171], v205 offset:53504
	ds_read_b128 v[188:191], v207 offset:36864
	ds_read_b128 v[192:195], v207 offset:38912
	ds_read_b128 v[196:199], v207 offset:40960
	ds_read_b128 v[200:203], v207 offset:43008
	s_waitcnt lgkmcnt(8)
	v_mfma_f32_16x16x32_bf16 v[16:19], v[100:103], v[84:87], v[16:19]
	global_load_lds_dwordx4 v212, s[2:3]
	s_add_u32 m0, s13, 0x5000
	v_mfma_f32_16x16x32_bf16 v[20:23], v[104:107], v[84:87], v[20:23]
	global_load_lds_dwordx4 v213, s[6:7]
	s_add_u32 m0, s13, 0x6000
	v_mfma_f32_16x16x32_bf16 v[24:27], v[108:111], v[84:87], v[24:27]
	global_load_lds_dwordx4 v214, s[6:7]
	s_add_u32 m0, s13, 0x7000
	v_mfma_f32_16x16x32_bf16 v[28:31], v[112:115], v[84:87], v[28:31]
	global_load_lds_dwordx4 v215, s[6:7]
	s_add_u32 m0, s13, 0x8000
	ds_read_b128 v[172:175], v205 offset:55552
	ds_read_b128 v[176:179], v205 offset:57600
	ds_read_b128 v[180:183], v205 offset:59648
	ds_read_b128 v[184:187], v205 offset:61696
	s_waitcnt lgkmcnt(11)
	v_mfma_f32_16x16x32_bf16 v[32:35], v[100:103], v[88:91], v[32:35]
	global_load_lds_dwordx4 v216, s[6:7]
	v_mfma_f32_16x16x32_bf16 v[36:39], v[104:107], v[88:91], v[36:39]
	v_mfma_f32_16x16x32_bf16 v[40:43], v[108:111], v[88:91], v[40:43]
	v_mfma_f32_16x16x32_bf16 v[44:47], v[112:115], v[88:91], v[44:47]
	s_waitcnt lgkmcnt(10)
	v_mfma_f32_16x16x32_bf16 v[48:51], v[100:103], v[92:95], v[48:51]
	v_mfma_f32_16x16x32_bf16 v[52:55], v[104:107], v[92:95], v[52:55]
	v_mfma_f32_16x16x32_bf16 v[56:59], v[108:111], v[92:95], v[56:59]
	v_mfma_f32_16x16x32_bf16 v[60:63], v[112:115], v[92:95], v[60:63]
	s_waitcnt lgkmcnt(9)
	v_mfma_f32_16x16x32_bf16 v[64:67], v[100:103], v[96:99], v[64:67]
	v_mfma_f32_16x16x32_bf16 v[68:71], v[104:107], v[96:99], v[68:71]
	v_mfma_f32_16x16x32_bf16 v[72:75], v[108:111], v[96:99], v[72:75]
	v_mfma_f32_16x16x32_bf16 v[76:79], v[112:115], v[96:99], v[76:79]
	s_waitcnt lgkmcnt(7)
	v_mfma_f32_16x16x32_bf16 v[0:3], v[188:191], v[168:171], v[0:3]
	s_waitcnt lgkmcnt(6)
	v_mfma_f32_16x16x32_bf16 v[4:7], v[192:195], v[168:171], v[4:7]
	s_waitcnt lgkmcnt(5)
	v_mfma_f32_16x16x32_bf16 v[8:11], v[196:199], v[168:171], v[8:11]
	s_waitcnt lgkmcnt(4)
	v_mfma_f32_16x16x32_bf16 v[12:15], v[200:203], v[168:171], v[12:15]
	s_waitcnt lgkmcnt(3)
	v_mfma_f32_16x16x32_bf16 v[16:19], v[188:191], v[172:175], v[16:19]
	v_mfma_f32_16x16x32_bf16 v[20:23], v[192:195], v[172:175], v[20:23]
	v_mfma_f32_16x16x32_bf16 v[24:27], v[196:199], v[172:175], v[24:27]
	v_mfma_f32_16x16x32_bf16 v[28:31], v[200:203], v[172:175], v[28:31]
	s_waitcnt lgkmcnt(2)
	v_mfma_f32_16x16x32_bf16 v[32:35], v[188:191], v[176:179], v[32:35]
	v_mfma_f32_16x16x32_bf16 v[36:39], v[192:195], v[176:179], v[36:39]
	v_mfma_f32_16x16x32_bf16 v[40:43], v[196:199], v[176:179], v[40:43]
	v_mfma_f32_16x16x32_bf16 v[44:47], v[200:203], v[176:179], v[44:47]
	s_waitcnt lgkmcnt(1)
	v_mfma_f32_16x16x32_bf16 v[48:51], v[188:191], v[180:183], v[48:51]
	v_mfma_f32_16x16x32_bf16 v[52:55], v[192:195], v[180:183], v[52:55]
	v_mfma_f32_16x16x32_bf16 v[56:59], v[196:199], v[180:183], v[56:59]
	v_mfma_f32_16x16x32_bf16 v[60:63], v[200:203], v[180:183], v[60:63]
	s_add_u32 s2, s2, 0x80
	s_addc_u32 s3, s3, 0
	s_add_u32 s6, s6, 0x80
	s_addc_u32 s7, s7, 0
	s_waitcnt lgkmcnt(0)
	v_mfma_f32_16x16x32_bf16 v[64:67], v[188:191], v[184:187], v[64:67]
	v_mfma_f32_16x16x32_bf16 v[68:71], v[192:195], v[184:187], v[68:71]
	v_mfma_f32_16x16x32_bf16 v[72:75], v[196:199], v[184:187], v[72:75]
	v_mfma_f32_16x16x32_bf16 v[76:79], v[200:203], v[184:187], v[76:79]
	s_sub_u32 s12, s12, 1
	s_cmp_lg_u32 s12, 0
	s_cbranch_scc1 .Lgzin_pair
	s_and_b32 s4, s10, 7
	s_lshl_b32 s4, s4, 3
	s_bfe_u32 s14, s10, 0x30003
	s_or_b32 s14, s14, s4
	s_lshr_b32 s15, s10, 6
	s_mul_i32 s44, s14, 0xa0
	s_mul_i32 s4, s35, 0x50
	s_add_u32 s4, s4, s44
	v_add_u32_e32 v219, s4, v222
	s_nop 7
	s_lshl_b32 s46, s15, 7
	s_lshl_b32 s4, s36, 6
	s_add_u32 s46, s46, s4
	s_cmp_ge_u32 s46, 0xbc0
	s_cbranch_scc1 .Lgzin_z0_end
	s_cmp_lt_u32 s46, 0x200
	s_cbranch_scc1 .Lgzin_z0_q
	s_cmp_lt_u32 s46, 0x600
	s_cbranch_scc1 .Lgzin_z0_kv
	s_cmp_lt_u32 s46, 0x800
	s_cbranch_scc1 .Lgzin_z0_u
	s_mul_i32 s4, s44, 0x2f00
	s_lshl_b32 s32, s46, 2
	s_add_u32 s4, s4, s32
	s_add_u32 s8, s74, s4
	s_addc_u32 s9, s75, 0
	global_store_dwordx4 v218, v[0:3], s[8:9]
	global_store_dwordx4 v218, v[4:7], s[8:9] offset:16
	s_add_u32 s8, s8, 0x2f000
	s_addc_u32 s9, s9, 0
	global_store_dwordx4 v218, v[16:19], s[8:9]
	global_store_dwordx4 v218, v[20:23], s[8:9] offset:16
	s_add_u32 s8, s8, 0x2f000
	s_addc_u32 s9, s9, 0
	global_store_dwordx4 v218, v[32:35], s[8:9]
	global_store_dwordx4 v218, v[36:39], s[8:9] offset:16
	s_add_u32 s8, s8, 0x2f000
	s_addc_u32 s9, s9, 0
	global_store_dwordx4 v218, v[48:51], s[8:9]
	global_store_dwordx4 v218, v[52:55], s[8:9] offset:16
	s_add_u32 s8, s8, 0x2f000
	s_addc_u32 s9, s9, 0
	global_store_dwordx4 v218, v[64:67], s[8:9]
	global_store_dwordx4 v218, v[68:71], s[8:9] offset:16
	s_branch .Lgzin_z0_end

.LBB0_608:
	s_or_b64 exec, exec, s[20:21]
	s_waitcnt lgkmcnt(0)
	s_barrier
	ds_read_b32 v0, v117 offset:53264
	v_readlane_b32 s2, v162, 25
	s_mov_b64 s[20:21], -1
	s_waitcnt lgkmcnt(0)
	v_readfirstlane_b32 s35, v0
	v_cmp_le_i32_e32 vcc, s2, v0
	s_cbranch_vccnz .LBB0_603
	s_cmp_gt_i32 s35, 63
	s_cbranch_scc0 .LBB0_739
	s_cmpk_gt_u32 s35, 0x23f
	s_cbranch_scc0 .LBB0_723
	s_cmpk_gt_u32 s35, 0x33f
	s_cbranch_scc0 .LBB0_644
	s_cmpk_gt_u32 s35, 0x73f
	s_cbranch_scc0 .LBB0_639
	s_cmpk_gt_u32 s35, 0x87f
	s_cbranch_scc0 .LBB0_634
	s_sub_u32 s35, s35, 2176
	s_lshl_b32 s35, s35, 3
	s_add_u32 s35, s35, 2176
	s_mov_b32 s53, 0
.Ltr_again:
	s_add_i32 s2, s35, 0xfffff780
	s_cmpk_lt_u32 s2, 0x18c0
	s_movk_i32 s3, 0x840
	s_cselect_b32 s3, s3, 0xb40
	s_cmpk_gt_u32 s2, 0x107f
	s_cselect_b32 s40, s3, 0x580
	s_add_i32 s40, s40, s2
	s_cmpk_gt_u32 s40, 0x15ff
	s_mov_b64 s[38:39], -1
	s_cbranch_scc0 .LBB0_623
	s_cmpk_gt_u32 s40, 0x20ff
	s_mov_b64 s[22:23], -1
	s_cbranch_scc0 .LBB0_620
	s_cmpk_gt_u32 s40, 0x26ff
	s_cbranch_scc0 .LBB0_618
	v_readlane_b32 s4, v164, 17
	s_add_i32 s2, s40, 0xffffd900
	v_readlane_b32 s8, v164, 21
	v_readlane_b32 s9, v164, 22
	v_readlane_b32 s10, v164, 23
	v_readlane_b32 s11, v164, 24
	v_readlane_b32 s12, v164, 25
	v_readlane_b32 s13, v164, 26
	v_readlane_b32 s14, v164, 27
	v_readlane_b32 s15, v164, 28
	s_lshr_b32 s36, s2, 8
	v_readlane_b32 s16, v164, 29
	v_readlane_b32 s17, v164, 30
	v_readlane_b32 s18, v164, 31
	v_readlane_b32 s19, v164, 32
	s_mov_b64 s[8:9], s[12:13]
	s_and_b32 s3, s40, 0xff
	s_lshl_b64 s[20:21], s[36:37], 22
	s_mov_b64 s[10:11], s[14:15]
	s_mov_b64 s[12:13], s[16:17]
	v_readlane_b32 s5, v164, 18
	v_readlane_b32 s6, v164, 19
	v_readlane_b32 s7, v164, 20
	s_mov_b64 s[14:15], s[18:19]
	s_add_u32 s24, s12, s20
	s_addc_u32 s25, s13, s21
	v_readlane_b32 s4, v163, 1
	s_lshl_b64 s[20:21], s[36:37], 21
	v_readlane_b32 s14, v163, 11
	v_readlane_b32 s15, v163, 12
	s_add_u32 s20, s14, s20
	v_readlane_b32 s5, v163, 2
	v_readlane_b32 s6, v163, 3
	v_readlane_b32 s7, v163, 4
	v_readlane_b32 s8, v163, 5
	v_readlane_b32 s9, v163, 6
	v_readlane_b32 s10, v163, 7
	v_readlane_b32 s11, v163, 8
	v_readlane_b32 s12, v163, 9
	v_readlane_b32 s13, v163, 10
	v_readlane_b32 s16, v163, 13
	v_readlane_b32 s17, v163, 14
	v_readlane_b32 s18, v163, 15
	v_readlane_b32 s19, v163, 16
	s_addc_u32 s21, s15, s21
	s_mov_b64 s[22:23], 0

.LBB0_625:
	s_and_b32 s38, 0xffff, s36
	v_cvt_f32_u32_e32 v0, s38
	s_and_b32 s38, s3, 0xffff
	v_cvt_f32_u32_e32 v1, s38
	s_waitcnt vmcnt(5)
	v_mov_b32_e32 v8, v128
	v_rcp_iflag_f32_e32 v2, v0
	v_mov_b32_e32 v4, 0
	v_ashrrev_i32_e32 v9, 4, v8
	v_mul_f32_e32 v2, v1, v2
	v_trunc_f32_e32 v2, v2
	v_cvt_u32_f32_e32 v3, v2
	v_fma_f32 v1, -v2, v0, v1
	v_cmp_ge_f32_e64 s[38:39], |v1|, v0
	s_cmp_lg_u64 s[38:39], 0
	v_readfirstlane_b32 s38, v3
	s_addc_u32 s38, s38, 0
	s_and_b32 s39, s38, 0xffff
	s_mul_i32 s38, s38, s36
	s_sub_i32 s3, s3, s38
	s_lshl_b32 s3, s3, 6
	v_lshlrev_b32_e32 v0, 2, v8
	s_and_b32 s3, s3, 0xffc0
	v_and_b32_e32 v1, 60, v0
	v_or_b32_e32 v0, s3, v1
	v_lshlrev_b32_e32 v116, 2, v0
	s_lshl_b32 s36, s39, 6
	v_cmp_gt_u32_e32 vcc, s2, v0
	v_lshl_add_u64 v[6:7], s[24:25], 0, v[116:117]
	v_mov_b32_e32 v168, 0
	v_mov_b32_e32 v169, 0
	v_mov_b32_e32 v170, 0
	v_mov_b32_e32 v171, 0
	v_mov_b32_e32 v172, 0
	v_mov_b32_e32 v173, 0
	v_mov_b32_e32 v174, 0
	v_mov_b32_e32 v175, 0
	v_mov_b32_e32 v176, 0
	v_mov_b32_e32 v177, 0
	v_mov_b32_e32 v178, 0
	v_mov_b32_e32 v179, 0
	v_mov_b32_e32 v180, 0
	v_mov_b32_e32 v181, 0
	v_mov_b32_e32 v182, 0
	v_mov_b32_e32 v183, 0
	v_mov_b32_e32 v185, 0
	s_lshl_b32 s50, s2, 6
	s_mov_b32 s51, 0
	s_and_saveexec_b64 s[24:25], vcc
	s_cbranch_execz .Ltrp_1
	v_add_u32_e32 v184, s36, v9
	v_mul_lo_u32 v184, v184, s2
	v_lshlrev_b32_e32 v184, 2, v184
	v_lshl_add_u64 v[186:187], v[184:185], 0, v[6:7]
	global_load_dwordx4 v[168:171], v[186:187], off nt
	v_lshl_add_u64 v[186:187], v[186:187], 0, s[50:51]
	global_load_dwordx4 v[172:175], v[186:187], off nt
	v_lshl_add_u64 v[186:187], v[186:187], 0, s[50:51]
	global_load_dwordx4 v[176:179], v[186:187], off nt
	v_lshl_add_u64 v[186:187], v[186:187], 0, s[50:51]
	global_load_dwordx4 v[180:183], v[186:187], off nt
.Ltrp_1:
	s_or_b64 exec, exec, s[24:25]
	s_movk_i32 s4, 0x104
	v_lshlrev_b32_e32 v1, 2, v1
	v_mul_lo_u32 v10, v9, s4
	v_add_u32_e32 v10, v1, v10
	s_waitcnt vmcnt(0)
	ds_write2_b32 v10, v168, v169 offset1:1
	ds_write2_b32 v10, v170, v171 offset0:2 offset1:3
	v_add_u32_e32 v4, 0x1040, v10
	ds_write2_b32 v4, v172, v173 offset1:1
	v_add_u32_e32 v0, 0x1048, v10
	ds_write2_b32 v0, v174, v175 offset1:1
	v_add_u32_e32 v1, 0x2080, v10
	ds_write2_b32 v1, v176, v177 offset1:1
	v_add_u32_e32 v2, 0x2088, v10
	ds_write2_b32 v2, v178, v179 offset1:1
	v_add_u32_e32 v3, 0x30c0, v10
	ds_write2_b32 v3, v180, v181 offset1:1
	v_add_u32_e32 v5, 0x30c8, v10
	ds_write2_b32 v5, v182, v183 offset1:1
	v_lshlrev_b32_e32 v0, 4, v8
	v_and_b32_e32 v18, 48, v0
	v_and_b32_e32 v0, -4, v8
	s_movk_i32 s2, 0x104
	v_mad_u32_u24 v12, v18, s2, v0
	s_waitcnt lgkmcnt(0)
	s_barrier
	ds_read2_b32 v[0:1], v12 offset1:65
	ds_read2_b32 v[2:3], v12 offset0:130 offset1:195
	v_ashrrev_i32_e32 v16, 2, v8
	v_add_u32_e32 v6, 0x400, v12
	v_add_u32_e32 v16, s3, v16
	ds_read2_b32 v[4:5], v6 offset0:4 offset1:69
	ds_read2_b32 v[6:7], v6 offset0:134 offset1:199
	v_ashrrev_i32_e32 v17, 31, v16
	v_mul_lo_u32 v19, s22, v17
	v_mul_lo_u32 v20, s23, v16
	v_mad_u64_u32 v[16:17], s[2:3], s22, v16, 0
	v_lshlrev_b32_e32 v116, 1, v18
	s_waitcnt lgkmcnt(2)
	v_and_b32_sdwa v18, v2, v129 dst_sel:DWORD dst_unused:UNUSED_PAD src0_sel:WORD_1 src1_sel:DWORD
	v_add3_u32 v17, v17, v19, v20
	v_and_b32_sdwa v19, v0, v129 dst_sel:DWORD dst_unused:UNUSED_PAD src0_sel:WORD_1 src1_sel:DWORD
	v_add3_u32 v2, v2, v18, s88
	v_and_b32_sdwa v18, v3, v129 dst_sel:DWORD dst_unused:UNUSED_PAD src0_sel:WORD_1 src1_sel:DWORD
	v_add3_u32 v0, v0, v19, s88
	v_and_b32_sdwa v19, v1, v129 dst_sel:DWORD dst_unused:UNUSED_PAD src0_sel:WORD_1 src1_sel:DWORD
	v_add3_u32 v3, v3, v18, s88
	v_add3_u32 v1, v1, v19, s88
	v_and_b32_e32 v3, 0xffff0000, v3
	v_add_u32_e32 v10, 0x800, v12
	v_and_b32_e32 v18, 0xffff0000, v1
	v_or_b32_sdwa v1, v3, v2 dst_sel:DWORD dst_unused:UNUSED_PAD src0_sel:DWORD src1_sel:WORD_1
	s_waitcnt lgkmcnt(0)
	v_and_b32_sdwa v2, v6, v129 dst_sel:DWORD dst_unused:UNUSED_PAD src0_sel:WORD_1 src1_sel:DWORD
	v_and_b32_sdwa v3, v4, v129 dst_sel:DWORD dst_unused:UNUSED_PAD src0_sel:WORD_1 src1_sel:DWORD
	ds_read2_b32 v[8:9], v10 offset0:8 offset1:73
	ds_read2_b32 v[10:11], v10 offset0:138 offset1:203
	v_add3_u32 v4, v4, v3, s88
	v_add3_u32 v2, v6, v2, s88
	v_and_b32_sdwa v3, v7, v129 dst_sel:DWORD dst_unused:UNUSED_PAD src0_sel:WORD_1 src1_sel:DWORD
	v_and_b32_sdwa v6, v5, v129 dst_sel:DWORD dst_unused:UNUSED_PAD src0_sel:WORD_1 src1_sel:DWORD
	v_lshl_add_u64 v[16:17], v[16:17], 1, s[20:21]
	s_lshl_b32 s36, s36, 1
	v_add3_u32 v3, v7, v3, s88
	v_add3_u32 v5, v5, v6, s88
	v_lshl_add_u64 v[16:17], v[16:17], 0, s[36:37]
	v_and_b32_e32 v3, 0xffff0000, v3
	v_and_b32_e32 v5, 0xffff0000, v5
	v_add_u32_e32 v14, 0xc00, v12
	v_lshl_add_u64 v[16:17], v[16:17], 0, v[116:117]
	v_or_b32_sdwa v0, v18, v0 dst_sel:DWORD dst_unused:UNUSED_PAD src0_sel:DWORD src1_sel:WORD_1
	v_or_b32_sdwa v3, v3, v2 dst_sel:DWORD dst_unused:UNUSED_PAD src0_sel:DWORD src1_sel:WORD_1
	v_or_b32_sdwa v2, v5, v4 dst_sel:DWORD dst_unused:UNUSED_PAD src0_sel:DWORD src1_sel:WORD_1
	ds_read2_b32 v[12:13], v14 offset0:12 offset1:77
	ds_read2_b32 v[14:15], v14 offset0:142 offset1:207
	global_store_dwordx4 v[16:17], v[0:3], off
	s_mov_b64 s[20:21], 0
	s_waitcnt lgkmcnt(1)
	v_and_b32_sdwa v5, v13, v129 dst_sel:DWORD dst_unused:UNUSED_PAD src0_sel:WORD_1 src1_sel:DWORD
	v_and_b32_sdwa v1, v8, v129 dst_sel:DWORD dst_unused:UNUSED_PAD src0_sel:WORD_1 src1_sel:DWORD
	v_add3_u32 v2, v8, v1, s88
	v_and_b32_sdwa v1, v11, v129 dst_sel:DWORD dst_unused:UNUSED_PAD src0_sel:WORD_1 src1_sel:DWORD
	v_and_b32_sdwa v3, v9, v129 dst_sel:DWORD dst_unused:UNUSED_PAD src0_sel:WORD_1 src1_sel:DWORD
	v_and_b32_sdwa v0, v10, v129 dst_sel:DWORD dst_unused:UNUSED_PAD src0_sel:WORD_1 src1_sel:DWORD
	v_add3_u32 v1, v11, v1, s88
	v_add3_u32 v3, v9, v3, s88
	v_add3_u32 v0, v10, v0, s88
	v_and_b32_e32 v1, 0xffff0000, v1
	v_and_b32_e32 v3, 0xffff0000, v3
	v_or_b32_sdwa v1, v1, v0 dst_sel:DWORD dst_unused:UNUSED_PAD src0_sel:DWORD src1_sel:WORD_1
	v_or_b32_sdwa v0, v3, v2 dst_sel:DWORD dst_unused:UNUSED_PAD src0_sel:DWORD src1_sel:WORD_1
	v_and_b32_sdwa v3, v12, v129 dst_sel:DWORD dst_unused:UNUSED_PAD src0_sel:WORD_1 src1_sel:DWORD
	v_add3_u32 v4, v12, v3, s88
	s_waitcnt lgkmcnt(0)
	v_and_b32_sdwa v3, v15, v129 dst_sel:DWORD dst_unused:UNUSED_PAD src0_sel:WORD_1 src1_sel:DWORD
	v_and_b32_sdwa v2, v14, v129 dst_sel:DWORD dst_unused:UNUSED_PAD src0_sel:WORD_1 src1_sel:DWORD
	v_add3_u32 v3, v15, v3, s88
	v_add3_u32 v5, v13, v5, s88
	v_add3_u32 v2, v14, v2, s88
	v_and_b32_e32 v3, 0xffff0000, v3
	v_and_b32_e32 v5, 0xffff0000, v5
	v_or_b32_sdwa v3, v3, v2 dst_sel:DWORD dst_unused:UNUSED_PAD src0_sel:DWORD src1_sel:WORD_1
	v_or_b32_sdwa v2, v5, v4 dst_sel:DWORD dst_unused:UNUSED_PAD src0_sel:DWORD src1_sel:WORD_1
	global_store_dwordx4 v[16:17], v[0:3], off offset:16
	s_barrier
	s_add_u32 s53, s53, 1
	s_cmp_lt_u32 s53, 8
	s_cbranch_scc0 .Ltr_done
	s_add_u32 s35, s35, 1
	s_branch .Ltr_again
.Ltr_done:
.LBB0_634:
	s_and_b64 vcc, exec, s[20:21]
	s_cbranch_vccz .LBB0_638
	s_lshl_b32 s2, s35, 5
	s_waitcnt vmcnt(2)
	v_mov_b32_e32 v42, v128
	s_addk_i32 s2, 0x1800
	s_and_b32 s24, s2, 0x3f80
	s_waitcnt vmcnt(1)
	v_ashrrev_i32_e32 v45, 1, v42
	v_add_u32_e32 v0, s24, v45
	v_ashrrev_i32_e32 v1, 31, v0
	v_and_b32_e32 v36, 1, v42
	v_lshlrev_b64 v[0:1], 10, v[0:1]
	v_lshl_add_u64 v[0:1], s[70:71], 0, v[0:1]
	v_lshlrev_b32_e32 v116, 8, v36
	v_mov_b32_e32 v4, 0
	s_barrier
	v_lshl_add_u64 v[2:3], v[0:1], 0, v[116:117]
	s_mov_b64 s[20:21], 0
	v_mov_b32_e32 v5, v4
